# v8 + accumulator zeroing folded into the epilogue blocks (hidden under the store issue), separate zeroing block removed
# baseline (speedup 1.0000x reference)
; __device__ __forceinline__ void gemm_phase(LAS unsigned char* lds, const GemmP g, const EpiP e) {
;     ...
; #pragma unroll
;         for (int a = 0; a < 2; ++a)
; #pragma unroll
;             for (int b = 0; b < 2; ++b)
; #pragma unroll
;                 for (int m = 0; m < 4; ++m)
; #pragma unroll
;                     for (int n = 0; n < 2; ++n) acc[a][b][m][n] = (f32x4){0.f, 0.f, 0.f, 0.f};
;         cur = nxt; cA = nA; cB = nB; ++ui;
.LBB0_370:
	v_mov_b32_e32 v96, v97
	v_mov_b32_e32 v98, v97
	v_mov_b32_e32 v99, v97
	v_readlane_b32 s69, v254, 57
	s_mov_b32 s42, s86
	s_mov_b32 s85, s68
	s_mov_b32 s87, s45
	s_mov_b64 s[40:41], s[80:81]
	s_mov_b64 s[78:79], s[50:51]
	s_mov_b32 s37, s84

; __device__ __forceinline__ unsigned cvt_pk_bf16(float lo, float hi) { unsigned r; asm volatile("v_cvt_pk_bf16_f32 %0, %1, %2" : "=v"(r) : "v"(lo), "v"(hi)); return r; }
; __device__ __forceinline__ void epi_store(const f32x4 (&acc)[2][2][4][2], const Unit& u, int wr, int wc, int fr, int fq, const EpiP& e) {
;     ...
;             for (int m = 0; m < 4; ++m) {
;                 const int row = row0 + ai * HALF + m * 16;
;                 f32x4 v0 = acc[ai][bj][m][0], v1 = acc[ai][bj][m][1];
;                 if (kind != 0 && row < MLAT) {
;                     const int t = row & (SEQ - 1); const int pos = (kind == 1) ? (t >> 6) : (t & 63);
;                     const f32x4 t0 = *(const f32x4*)(e.rope + (pos * 16 + 4 * fq) * 2), t1 = *(const f32x4*)(e.rope + (pos * 16 + 4 * fq) * 2 + 4);
;                     const float cs[4] = {t0[0], t0[2], t1[0], t1[2]}, sn[4] = {t0[1], t0[3], t1[1], t1[3]};
; #pragma unroll
;                     for (int j = 0; j < 4; ++j) { const float x1 = v0[j], x2 = v1[j]; v0[j] = x1 * cs[j] - x2 * sn[j]; v1[j] = x2 * cs[j] + x1 * sn[j]; }
;                 }
;                 bf16_t* rowp = e.O + (size_t)row * e.ldo + c;
;                 u32x2 w0, w1; w0.x = cvt_pk_bf16(v0[0], v0[1]); w0.y = cvt_pk_bf16(v0[2], v0[3]); w1.x = cvt_pk_bf16(v1[0], v1[1]); w1.y = cvt_pk_bf16(v1[2], v1[3]);
;                 const bool odd = (fq & 1) != 0;
;                 const unsigned sx = odd ? w0.x : w1.x, sy = odd ? w0.y : w1.y;
;                 const unsigned rx = (unsigned)__shfl_xor((int)sx, 16), ry = (unsigned)__shfl_xor((int)sy, 16);
;                 u32x4 w; if (odd) { w.x = rx; w.y = ry; w.z = w1.x; w.w = w1.y; } else { w.x = w0.x; w.y = w0.y; w.z = rx; w.w = ry; }
;                 *(u32x4*)(rowp + (odd ? 12 : 0)) = w;
; __device__ __forceinline__ void gemm_phase(LAS unsigned char* lds, const GemmP g, const EpiP e) {
;     ...
; #pragma unroll
;         for (int a = 0; a < 2; ++a)
; #pragma unroll
;             for (int b = 0; b < 2; ++b)
; #pragma unroll
;                 for (int m = 0; m < 4; ++m)
; #pragma unroll
;                     for (int n = 0; n < 2; ++n) acc[a][b][m][n] = (f32x4){0.f, 0.f, 0.f, 0.f};
.Lrp_loaded:
	s_cmp_eq_u32 s20, 0
	s_cbranch_scc1 .Lrp_plain0
	s_cmp_eq_u32 s20, 1
	s_cbranch_scc0 .Lrp_k2_0
	s_mov_b64 s[98:99], s[100:101]
	v_mul_f32_e32 v248, v124, v161
	v_mul_f32_e32 v249, v128, v161
	v_fma_f32 v240, v128, v160, -v248
	v_fma_f32 v244, v124, v160, v249
	v_mul_f32_e32 v248, v125, v163
	v_mul_f32_e32 v249, v129, v163
	v_fma_f32 v241, v129, v162, -v248
	v_fma_f32 v245, v125, v162, v249
	v_mul_f32_e32 v248, v126, v165
	v_mul_f32_e32 v249, v130, v165
	v_fma_f32 v242, v130, v164, -v248
	v_fma_f32 v246, v126, v164, v249
	v_mul_f32_e32 v248, v127, v167
	v_mul_f32_e32 v249, v131, v167
	v_fma_f32 v243, v131, v166, -v248
	v_fma_f32 v247, v127, v166, v249
	v_mov_b64_e32 v[128:129], 0
	v_mov_b64_e32 v[130:131], 0
	v_mov_b64_e32 v[124:125], 0
	v_mov_b64_e32 v[126:127], 0
	v_cvt_pk_bf16_f32 v204, v240, v241
	v_cvt_pk_bf16_f32 v205, v242, v243
	v_cvt_pk_bf16_f32 v206, v244, v245
	v_cvt_pk_bf16_f32 v207, v246, v247
	s_nop 1
	v_permlane16_swap_b32_e32 v204, v206
	v_permlane16_swap_b32_e32 v205, v207
	global_store_dwordx4 v216, v[204:207], s[98:99]
	s_mul_i32 s18, s19, 1
	s_add_u32 s98, s100, s18
	s_addc_u32 s99, s101, 0
	v_mul_f32_e32 v248, v116, v161
	v_mul_f32_e32 v249, v120, v161
	v_fma_f32 v240, v120, v160, -v248
	v_fma_f32 v244, v116, v160, v249
	v_mul_f32_e32 v248, v117, v163
	v_mul_f32_e32 v249, v121, v163
	v_fma_f32 v241, v121, v162, -v248
	v_fma_f32 v245, v117, v162, v249
	v_mul_f32_e32 v248, v118, v165
	v_mul_f32_e32 v249, v122, v165
	v_fma_f32 v242, v122, v164, -v248
	v_fma_f32 v246, v118, v164, v249
	v_mul_f32_e32 v248, v119, v167
	v_mul_f32_e32 v249, v123, v167
	v_fma_f32 v243, v123, v166, -v248
	v_fma_f32 v247, v119, v166, v249
	v_mov_b64_e32 v[120:121], 0
	v_mov_b64_e32 v[122:123], 0
	v_mov_b64_e32 v[116:117], 0
	v_mov_b64_e32 v[118:119], 0
	v_cvt_pk_bf16_f32 v132, v240, v241
	v_cvt_pk_bf16_f32 v133, v242, v243
	v_cvt_pk_bf16_f32 v134, v244, v245
	v_cvt_pk_bf16_f32 v135, v246, v247
	s_nop 1
	v_permlane16_swap_b32_e32 v132, v134
	v_permlane16_swap_b32_e32 v133, v135
	global_store_dwordx4 v216, v[132:135], s[98:99]
	s_mul_i32 s18, s19, 2
	s_add_u32 s98, s100, s18
	s_addc_u32 s99, s101, 0
	v_mul_f32_e32 v248, v108, v161
	v_mul_f32_e32 v249, v112, v161
	v_fma_f32 v240, v112, v160, -v248
	v_fma_f32 v244, v108, v160, v249
	v_mul_f32_e32 v248, v109, v163
	v_mul_f32_e32 v249, v113, v163
	v_fma_f32 v241, v113, v162, -v248
	v_fma_f32 v245, v109, v162, v249
	v_mul_f32_e32 v248, v110, v165
	v_mul_f32_e32 v249, v114, v165
	v_fma_f32 v242, v114, v164, -v248
	v_fma_f32 v246, v110, v164, v249
	v_mul_f32_e32 v248, v111, v167
	v_mul_f32_e32 v249, v115, v167
	v_fma_f32 v243, v115, v166, -v248
	v_fma_f32 v247, v111, v166, v249
	v_mov_b64_e32 v[112:113], 0
	v_mov_b64_e32 v[114:115], 0
	v_mov_b64_e32 v[108:109], 0
	v_mov_b64_e32 v[110:111], 0
	v_cvt_pk_bf16_f32 v136, v240, v241
	v_cvt_pk_bf16_f32 v137, v242, v243
	v_cvt_pk_bf16_f32 v138, v244, v245
	v_cvt_pk_bf16_f32 v139, v246, v247
	s_nop 1
	v_permlane16_swap_b32_e32 v136, v138
	v_permlane16_swap_b32_e32 v137, v139
	global_store_dwordx4 v216, v[136:139], s[98:99]
	s_mul_i32 s18, s19, 3
	s_add_u32 s98, s100, s18
	s_addc_u32 s99, s101, 0
	v_mul_f32_e32 v248, v100, v161
	v_mul_f32_e32 v249, v104, v161
	v_fma_f32 v240, v104, v160, -v248
	v_fma_f32 v244, v100, v160, v249
	v_mul_f32_e32 v248, v101, v163
	v_mul_f32_e32 v249, v105, v163
	v_fma_f32 v241, v105, v162, -v248
	v_fma_f32 v245, v101, v162, v249
	v_mul_f32_e32 v248, v102, v165
	v_mul_f32_e32 v249, v106, v165
	v_fma_f32 v242, v106, v164, -v248
	v_fma_f32 v246, v102, v164, v249
	v_mul_f32_e32 v248, v103, v167
	v_mul_f32_e32 v249, v107, v167
	v_fma_f32 v243, v107, v166, -v248
	v_fma_f32 v247, v103, v166, v249
	v_mov_b64_e32 v[104:105], 0
	v_mov_b64_e32 v[106:107], 0
	v_mov_b64_e32 v[100:101], 0
	v_mov_b64_e32 v[102:103], 0
	v_cvt_pk_bf16_f32 v204, v240, v241
	v_cvt_pk_bf16_f32 v205, v242, v243
	v_cvt_pk_bf16_f32 v206, v244, v245
	v_cvt_pk_bf16_f32 v207, v246, v247
	s_nop 1
	v_permlane16_swap_b32_e32 v204, v206
	v_permlane16_swap_b32_e32 v205, v207
	global_store_dwordx4 v216, v[204:207], s[98:99]
	s_mul_i32 s18, s19, 8
	s_add_u32 s98, s100, s18
	s_addc_u32 s99, s101, 0
	v_mul_f32_e32 v248, v56, v169
	v_mul_f32_e32 v249, v60, v169
	v_fma_f32 v240, v60, v168, -v248
	v_fma_f32 v244, v56, v168, v249
	v_mul_f32_e32 v248, v57, v171
	v_mul_f32_e32 v249, v61, v171
	v_fma_f32 v241, v61, v170, -v248
	v_fma_f32 v245, v57, v170, v249
	v_mul_f32_e32 v248, v58, v173
	v_mul_f32_e32 v249, v62, v173
	v_fma_f32 v242, v62, v172, -v248
	v_fma_f32 v246, v58, v172, v249
	v_mul_f32_e32 v248, v59, v175
	v_mul_f32_e32 v249, v63, v175
	v_fma_f32 v243, v63, v174, -v248
	v_fma_f32 v247, v59, v174, v249
	v_mov_b64_e32 v[60:61], 0
	v_mov_b64_e32 v[62:63], 0
	v_mov_b64_e32 v[56:57], 0
	v_mov_b64_e32 v[58:59], 0
	v_cvt_pk_bf16_f32 v132, v240, v241
	v_cvt_pk_bf16_f32 v133, v242, v243
	v_cvt_pk_bf16_f32 v134, v244, v245
	v_cvt_pk_bf16_f32 v135, v246, v247
	s_nop 1
	v_permlane16_swap_b32_e32 v132, v134
	v_permlane16_swap_b32_e32 v133, v135
	global_store_dwordx4 v216, v[132:135], s[98:99]
	s_mul_i32 s18, s19, 9
	s_add_u32 s98, s100, s18
	s_addc_u32 s99, s101, 0
	v_mul_f32_e32 v248, v48, v169
	v_mul_f32_e32 v249, v52, v169
	v_fma_f32 v240, v52, v168, -v248
	v_fma_f32 v244, v48, v168, v249
	v_mul_f32_e32 v248, v49, v171
	v_mul_f32_e32 v249, v53, v171
	v_fma_f32 v241, v53, v170, -v248
	v_fma_f32 v245, v49, v170, v249
	v_mul_f32_e32 v248, v50, v173
	v_mul_f32_e32 v249, v54, v173
	v_fma_f32 v242, v54, v172, -v248
	v_fma_f32 v246, v50, v172, v249
	v_mul_f32_e32 v248, v51, v175
	v_mul_f32_e32 v249, v55, v175
	v_fma_f32 v243, v55, v174, -v248
	v_fma_f32 v247, v51, v174, v249
; __device__ __forceinline__ unsigned cvt_pk_bf16(float lo, float hi) { unsigned r; asm volatile("v_cvt_pk_bf16_f32 %0, %1, %2" : "=v"(r) : "v"(lo), "v"(hi)); return r; }
; __device__ __forceinline__ void epi_store(const f32x4 (&acc)[2][2][4][2], const Unit& u, int wr, int wc, int fr, int fq, const EpiP& e) {
;     ...
;             for (int m = 0; m < 4; ++m) {
;                 const int row = row0 + ai * HALF + m * 16;
;                 f32x4 v0 = acc[ai][bj][m][0], v1 = acc[ai][bj][m][1];
;                 if (kind != 0 && row < MLAT) {
;                     const int t = row & (SEQ - 1); const int pos = (kind == 1) ? (t >> 6) : (t & 63);
;                     const f32x4 t0 = *(const f32x4*)(e.rope + (pos * 16 + 4 * fq) * 2), t1 = *(const f32x4*)(e.rope + (pos * 16 + 4 * fq) * 2 + 4);
;                     const float cs[4] = {t0[0], t0[2], t1[0], t1[2]}, sn[4] = {t0[1], t0[3], t1[1], t1[3]};
; #pragma unroll
;                     for (int j = 0; j < 4; ++j) { const float x1 = v0[j], x2 = v1[j]; v0[j] = x1 * cs[j] - x2 * sn[j]; v1[j] = x2 * cs[j] + x1 * sn[j]; }
;                 }
;                 bf16_t* rowp = e.O + (size_t)row * e.ldo + c;
;                 u32x2 w0, w1; w0.x = cvt_pk_bf16(v0[0], v0[1]); w0.y = cvt_pk_bf16(v0[2], v0[3]); w1.x = cvt_pk_bf16(v1[0], v1[1]); w1.y = cvt_pk_bf16(v1[2], v1[3]);
;                 const bool odd = (fq & 1) != 0;
;                 const unsigned sx = odd ? w0.x : w1.x, sy = odd ? w0.y : w1.y;
;                 const unsigned rx = (unsigned)__shfl_xor((int)sx, 16), ry = (unsigned)__shfl_xor((int)sy, 16);
;                 u32x4 w; if (odd) { w.x = rx; w.y = ry; w.z = w1.x; w.w = w1.y; } else { w.x = w0.x; w.y = w0.y; w.z = rx; w.w = ry; }
;                 *(u32x4*)(rowp + (odd ? 12 : 0)) = w;
; __device__ __forceinline__ void gemm_phase(LAS unsigned char* lds, const GemmP g, const EpiP e) {
;     ...
; #pragma unroll
;         for (int a = 0; a < 2; ++a)
; #pragma unroll
;             for (int b = 0; b < 2; ++b)
; #pragma unroll
;                 for (int m = 0; m < 4; ++m)
; #pragma unroll
;                     for (int n = 0; n < 2; ++n) acc[a][b][m][n] = (f32x4){0.f, 0.f, 0.f, 0.f};
	v_mov_b64_e32 v[52:53], 0
	v_mov_b64_e32 v[54:55], 0
	v_mov_b64_e32 v[48:49], 0
	v_mov_b64_e32 v[50:51], 0
	v_cvt_pk_bf16_f32 v136, v240, v241
	v_cvt_pk_bf16_f32 v137, v242, v243
	v_cvt_pk_bf16_f32 v138, v244, v245
	v_cvt_pk_bf16_f32 v139, v246, v247
	s_nop 1
	v_permlane16_swap_b32_e32 v136, v138
	v_permlane16_swap_b32_e32 v137, v139
	global_store_dwordx4 v216, v[136:139], s[98:99]
	s_mul_i32 s18, s19, 10
	s_add_u32 s98, s100, s18
	s_addc_u32 s99, s101, 0
	v_mul_f32_e32 v248, v40, v169
	v_mul_f32_e32 v249, v44, v169
	v_fma_f32 v240, v44, v168, -v248
	v_fma_f32 v244, v40, v168, v249
	v_mul_f32_e32 v248, v41, v171
	v_mul_f32_e32 v249, v45, v171
	v_fma_f32 v241, v45, v170, -v248
	v_fma_f32 v245, v41, v170, v249
	v_mul_f32_e32 v248, v42, v173
	v_mul_f32_e32 v249, v46, v173
	v_fma_f32 v242, v46, v172, -v248
	v_fma_f32 v246, v42, v172, v249
	v_mul_f32_e32 v248, v43, v175
	v_mul_f32_e32 v249, v47, v175
	v_fma_f32 v243, v47, v174, -v248
	v_fma_f32 v247, v43, v174, v249
	v_mov_b64_e32 v[44:45], 0
	v_mov_b64_e32 v[46:47], 0
	v_mov_b64_e32 v[40:41], 0
	v_mov_b64_e32 v[42:43], 0
	v_cvt_pk_bf16_f32 v204, v240, v241
	v_cvt_pk_bf16_f32 v205, v242, v243
	v_cvt_pk_bf16_f32 v206, v244, v245
	v_cvt_pk_bf16_f32 v207, v246, v247
	s_nop 1
	v_permlane16_swap_b32_e32 v204, v206
	v_permlane16_swap_b32_e32 v205, v207
	global_store_dwordx4 v216, v[204:207], s[98:99]
	s_mul_i32 s18, s19, 11
	s_add_u32 s98, s100, s18
	s_addc_u32 s99, s101, 0
	v_mul_f32_e32 v248, v32, v169
	v_mul_f32_e32 v249, v36, v169
	v_fma_f32 v240, v36, v168, -v248
	v_fma_f32 v244, v32, v168, v249
	v_mul_f32_e32 v248, v33, v171
	v_mul_f32_e32 v249, v37, v171
	v_fma_f32 v241, v37, v170, -v248
	v_fma_f32 v245, v33, v170, v249
	v_mul_f32_e32 v248, v34, v173
	v_mul_f32_e32 v249, v38, v173
	v_fma_f32 v242, v38, v172, -v248
	v_fma_f32 v246, v34, v172, v249
	v_mul_f32_e32 v248, v35, v175
	v_mul_f32_e32 v249, v39, v175
	v_fma_f32 v243, v39, v174, -v248
	v_fma_f32 v247, v35, v174, v249
	v_mov_b64_e32 v[36:37], 0
	v_mov_b64_e32 v[38:39], 0
	v_mov_b64_e32 v[32:33], 0
	v_mov_b64_e32 v[34:35], 0
	v_cvt_pk_bf16_f32 v132, v240, v241
	v_cvt_pk_bf16_f32 v133, v242, v243
	v_cvt_pk_bf16_f32 v134, v244, v245
	v_cvt_pk_bf16_f32 v135, v246, v247
	s_nop 1
	v_permlane16_swap_b32_e32 v132, v134
	v_permlane16_swap_b32_e32 v133, v135
	global_store_dwordx4 v216, v[132:135], s[98:99]
	s_branch .Lrp_end0
.Lrp_k2_0:
	s_mov_b64 s[98:99], s[100:101]
	v_mul_f32_e32 v248, v124, v161
	v_mul_f32_e32 v249, v128, v161
	v_fma_f32 v240, v128, v160, -v248
	v_fma_f32 v244, v124, v160, v249
	v_mul_f32_e32 v248, v125, v163
	v_mul_f32_e32 v249, v129, v163
	v_fma_f32 v241, v129, v162, -v248
	v_fma_f32 v245, v125, v162, v249
	v_mul_f32_e32 v248, v126, v165
	v_mul_f32_e32 v249, v130, v165
	v_fma_f32 v242, v130, v164, -v248
	v_fma_f32 v246, v126, v164, v249
	v_mul_f32_e32 v248, v127, v167
	v_mul_f32_e32 v249, v131, v167
	v_fma_f32 v243, v131, v166, -v248
	v_fma_f32 v247, v127, v166, v249
	v_mov_b64_e32 v[128:129], 0
	v_mov_b64_e32 v[130:131], 0
	v_mov_b64_e32 v[124:125], 0
	v_mov_b64_e32 v[126:127], 0
	v_cvt_pk_bf16_f32 v136, v240, v241
	v_cvt_pk_bf16_f32 v137, v242, v243
	v_cvt_pk_bf16_f32 v138, v244, v245
	v_cvt_pk_bf16_f32 v139, v246, v247
	s_nop 1
	v_permlane16_swap_b32_e32 v136, v138
	v_permlane16_swap_b32_e32 v137, v139
	global_store_dwordx4 v216, v[136:139], s[98:99]
	s_mul_i32 s18, s19, 1
	s_add_u32 s98, s100, s18
	s_addc_u32 s99, s101, 0
	v_mul_f32_e32 v248, v116, v169
	v_mul_f32_e32 v249, v120, v169
	v_fma_f32 v240, v120, v168, -v248
	v_fma_f32 v244, v116, v168, v249
	v_mul_f32_e32 v248, v117, v171
	v_mul_f32_e32 v249, v121, v171
	v_fma_f32 v241, v121, v170, -v248
	v_fma_f32 v245, v117, v170, v249
	v_mul_f32_e32 v248, v118, v173
	v_mul_f32_e32 v249, v122, v173
	v_fma_f32 v242, v122, v172, -v248
	v_fma_f32 v246, v118, v172, v249
	v_mul_f32_e32 v248, v119, v175
	v_mul_f32_e32 v249, v123, v175
	v_fma_f32 v243, v123, v174, -v248
	v_fma_f32 v247, v119, v174, v249
	v_mov_b64_e32 v[120:121], 0
	v_mov_b64_e32 v[122:123], 0
	v_mov_b64_e32 v[116:117], 0
	v_mov_b64_e32 v[118:119], 0
	v_cvt_pk_bf16_f32 v204, v240, v241
	v_cvt_pk_bf16_f32 v205, v242, v243
	v_cvt_pk_bf16_f32 v206, v244, v245
	v_cvt_pk_bf16_f32 v207, v246, v247
	s_nop 1
	v_permlane16_swap_b32_e32 v204, v206
	v_permlane16_swap_b32_e32 v205, v207
	global_store_dwordx4 v216, v[204:207], s[98:99]
	s_mul_i32 s18, s19, 2
	s_add_u32 s98, s100, s18
	s_addc_u32 s99, s101, 0
	v_mul_f32_e32 v248, v108, v225
	v_mul_f32_e32 v249, v112, v225
	v_fma_f32 v240, v112, v224, -v248
	v_fma_f32 v244, v108, v224, v249
	v_mul_f32_e32 v248, v109, v227
	v_mul_f32_e32 v249, v113, v227
	v_fma_f32 v241, v113, v226, -v248
	v_fma_f32 v245, v109, v226, v249
	v_mul_f32_e32 v248, v110, v229
	v_mul_f32_e32 v249, v114, v229
	v_fma_f32 v242, v114, v228, -v248
	v_fma_f32 v246, v110, v228, v249
	v_mul_f32_e32 v248, v111, v231
	v_mul_f32_e32 v249, v115, v231
	v_fma_f32 v243, v115, v230, -v248
	v_fma_f32 v247, v111, v230, v249
	v_mov_b64_e32 v[112:113], 0
	v_mov_b64_e32 v[114:115], 0
	v_mov_b64_e32 v[108:109], 0
	v_mov_b64_e32 v[110:111], 0
	v_cvt_pk_bf16_f32 v132, v240, v241
	v_cvt_pk_bf16_f32 v133, v242, v243
	v_cvt_pk_bf16_f32 v134, v244, v245
	v_cvt_pk_bf16_f32 v135, v246, v247
	s_nop 1
	v_permlane16_swap_b32_e32 v132, v134
	v_permlane16_swap_b32_e32 v133, v135
	global_store_dwordx4 v216, v[132:135], s[98:99]
	s_mul_i32 s18, s19, 3
	s_add_u32 s98, s100, s18
	s_addc_u32 s99, s101, 0
	v_mul_f32_e32 v248, v100, v233
	v_mul_f32_e32 v249, v104, v233
	v_fma_f32 v240, v104, v232, -v248
	v_fma_f32 v244, v100, v232, v249
	v_mul_f32_e32 v248, v101, v235
	v_mul_f32_e32 v249, v105, v235
	v_fma_f32 v241, v105, v234, -v248
; __device__ __forceinline__ unsigned cvt_pk_bf16(float lo, float hi) { unsigned r; asm volatile("v_cvt_pk_bf16_f32 %0, %1, %2" : "=v"(r) : "v"(lo), "v"(hi)); return r; }
; __device__ __forceinline__ void epi_store(const f32x4 (&acc)[2][2][4][2], const Unit& u, int wr, int wc, int fr, int fq, const EpiP& e) {
;     ...
;             for (int m = 0; m < 4; ++m) {
;                 const int row = row0 + ai * HALF + m * 16;
;                 f32x4 v0 = acc[ai][bj][m][0], v1 = acc[ai][bj][m][1];
;                 if (kind != 0 && row < MLAT) {
;                     const int t = row & (SEQ - 1); const int pos = (kind == 1) ? (t >> 6) : (t & 63);
;                     const f32x4 t0 = *(const f32x4*)(e.rope + (pos * 16 + 4 * fq) * 2), t1 = *(const f32x4*)(e.rope + (pos * 16 + 4 * fq) * 2 + 4);
;                     const float cs[4] = {t0[0], t0[2], t1[0], t1[2]}, sn[4] = {t0[1], t0[3], t1[1], t1[3]};
; #pragma unroll
;                     for (int j = 0; j < 4; ++j) { const float x1 = v0[j], x2 = v1[j]; v0[j] = x1 * cs[j] - x2 * sn[j]; v1[j] = x2 * cs[j] + x1 * sn[j]; }
;                 }
;                 bf16_t* rowp = e.O + (size_t)row * e.ldo + c;
;                 u32x2 w0, w1; w0.x = cvt_pk_bf16(v0[0], v0[1]); w0.y = cvt_pk_bf16(v0[2], v0[3]); w1.x = cvt_pk_bf16(v1[0], v1[1]); w1.y = cvt_pk_bf16(v1[2], v1[3]);
;                 const bool odd = (fq & 1) != 0;
;                 const unsigned sx = odd ? w0.x : w1.x, sy = odd ? w0.y : w1.y;
;                 const unsigned rx = (unsigned)__shfl_xor((int)sx, 16), ry = (unsigned)__shfl_xor((int)sy, 16);
;                 u32x4 w; if (odd) { w.x = rx; w.y = ry; w.z = w1.x; w.w = w1.y; } else { w.x = w0.x; w.y = w0.y; w.z = rx; w.w = ry; }
;                 *(u32x4*)(rowp + (odd ? 12 : 0)) = w;
; __device__ __forceinline__ void gemm_phase(LAS unsigned char* lds, const GemmP g, const EpiP e) {
;     ...
; #pragma unroll
;         for (int a = 0; a < 2; ++a)
; #pragma unroll
;             for (int b = 0; b < 2; ++b)
; #pragma unroll
;                 for (int m = 0; m < 4; ++m)
; #pragma unroll
;                     for (int n = 0; n < 2; ++n) acc[a][b][m][n] = (f32x4){0.f, 0.f, 0.f, 0.f};
	v_fma_f32 v245, v101, v234, v249
	v_mul_f32_e32 v248, v102, v237
	v_mul_f32_e32 v249, v106, v237
	v_fma_f32 v242, v106, v236, -v248
	v_fma_f32 v246, v102, v236, v249
	v_mul_f32_e32 v248, v103, v239
	v_mul_f32_e32 v249, v107, v239
	v_fma_f32 v243, v107, v238, -v248
	v_fma_f32 v247, v103, v238, v249
	v_mov_b64_e32 v[104:105], 0
	v_mov_b64_e32 v[106:107], 0
	v_mov_b64_e32 v[100:101], 0
	v_mov_b64_e32 v[102:103], 0
	v_cvt_pk_bf16_f32 v136, v240, v241
	v_cvt_pk_bf16_f32 v137, v242, v243
	v_cvt_pk_bf16_f32 v138, v244, v245
	v_cvt_pk_bf16_f32 v139, v246, v247
	s_nop 1
	v_permlane16_swap_b32_e32 v136, v138
	v_permlane16_swap_b32_e32 v137, v139
	global_store_dwordx4 v216, v[136:139], s[98:99]
	s_mul_i32 s18, s19, 8
	s_add_u32 s98, s100, s18
	s_addc_u32 s99, s101, 0
	v_mul_f32_e32 v248, v56, v161
	v_mul_f32_e32 v249, v60, v161
	v_fma_f32 v240, v60, v160, -v248
	v_fma_f32 v244, v56, v160, v249
	v_mul_f32_e32 v248, v57, v163
	v_mul_f32_e32 v249, v61, v163
	v_fma_f32 v241, v61, v162, -v248
	v_fma_f32 v245, v57, v162, v249
	v_mul_f32_e32 v248, v58, v165
	v_mul_f32_e32 v249, v62, v165
	v_fma_f32 v242, v62, v164, -v248
	v_fma_f32 v246, v58, v164, v249
	v_mul_f32_e32 v248, v59, v167
	v_mul_f32_e32 v249, v63, v167
	v_fma_f32 v243, v63, v166, -v248
	v_fma_f32 v247, v59, v166, v249
	v_mov_b64_e32 v[60:61], 0
	v_mov_b64_e32 v[62:63], 0
	v_mov_b64_e32 v[56:57], 0
	v_mov_b64_e32 v[58:59], 0
	v_cvt_pk_bf16_f32 v204, v240, v241
	v_cvt_pk_bf16_f32 v205, v242, v243
	v_cvt_pk_bf16_f32 v206, v244, v245
	v_cvt_pk_bf16_f32 v207, v246, v247
	s_nop 1
	v_permlane16_swap_b32_e32 v204, v206
	v_permlane16_swap_b32_e32 v205, v207
	global_store_dwordx4 v216, v[204:207], s[98:99]
	s_mul_i32 s18, s19, 9
	s_add_u32 s98, s100, s18
	s_addc_u32 s99, s101, 0
	v_mul_f32_e32 v248, v48, v169
	v_mul_f32_e32 v249, v52, v169
	v_fma_f32 v240, v52, v168, -v248
	v_fma_f32 v244, v48, v168, v249
	v_mul_f32_e32 v248, v49, v171
	v_mul_f32_e32 v249, v53, v171
	v_fma_f32 v241, v53, v170, -v248
	v_fma_f32 v245, v49, v170, v249
	v_mul_f32_e32 v248, v50, v173
	v_mul_f32_e32 v249, v54, v173
	v_fma_f32 v242, v54, v172, -v248
	v_fma_f32 v246, v50, v172, v249
	v_mul_f32_e32 v248, v51, v175
	v_mul_f32_e32 v249, v55, v175
	v_fma_f32 v243, v55, v174, -v248
	v_fma_f32 v247, v51, v174, v249
	v_mov_b64_e32 v[52:53], 0
	v_mov_b64_e32 v[54:55], 0
	v_mov_b64_e32 v[48:49], 0
	v_mov_b64_e32 v[50:51], 0
	v_cvt_pk_bf16_f32 v132, v240, v241
	v_cvt_pk_bf16_f32 v133, v242, v243
	v_cvt_pk_bf16_f32 v134, v244, v245
	v_cvt_pk_bf16_f32 v135, v246, v247
	s_nop 1
	v_permlane16_swap_b32_e32 v132, v134
	v_permlane16_swap_b32_e32 v133, v135
	global_store_dwordx4 v216, v[132:135], s[98:99]
	s_mul_i32 s18, s19, 10
	s_add_u32 s98, s100, s18
	s_addc_u32 s99, s101, 0
	v_mul_f32_e32 v248, v40, v225
	v_mul_f32_e32 v249, v44, v225
	v_fma_f32 v240, v44, v224, -v248
	v_fma_f32 v244, v40, v224, v249
	v_mul_f32_e32 v248, v41, v227
	v_mul_f32_e32 v249, v45, v227
	v_fma_f32 v241, v45, v226, -v248
	v_fma_f32 v245, v41, v226, v249
	v_mul_f32_e32 v248, v42, v229
	v_mul_f32_e32 v249, v46, v229
	v_fma_f32 v242, v46, v228, -v248
	v_fma_f32 v246, v42, v228, v249
	v_mul_f32_e32 v248, v43, v231
	v_mul_f32_e32 v249, v47, v231
	v_fma_f32 v243, v47, v230, -v248
	v_fma_f32 v247, v43, v230, v249
	v_mov_b64_e32 v[44:45], 0
	v_mov_b64_e32 v[46:47], 0
	v_mov_b64_e32 v[40:41], 0
	v_mov_b64_e32 v[42:43], 0
	v_cvt_pk_bf16_f32 v136, v240, v241
	v_cvt_pk_bf16_f32 v137, v242, v243
	v_cvt_pk_bf16_f32 v138, v244, v245
	v_cvt_pk_bf16_f32 v139, v246, v247
	s_nop 1
	v_permlane16_swap_b32_e32 v136, v138
	v_permlane16_swap_b32_e32 v137, v139
	global_store_dwordx4 v216, v[136:139], s[98:99]
	s_mul_i32 s18, s19, 11
	s_add_u32 s98, s100, s18
	s_addc_u32 s99, s101, 0
	v_mul_f32_e32 v248, v32, v233
	v_mul_f32_e32 v249, v36, v233
	v_fma_f32 v240, v36, v232, -v248
	v_fma_f32 v244, v32, v232, v249
	v_mul_f32_e32 v248, v33, v235
	v_mul_f32_e32 v249, v37, v235
	v_fma_f32 v241, v37, v234, -v248
	v_fma_f32 v245, v33, v234, v249
	v_mul_f32_e32 v248, v34, v237
	v_mul_f32_e32 v249, v38, v237
	v_fma_f32 v242, v38, v236, -v248
	v_fma_f32 v246, v34, v236, v249
	v_mul_f32_e32 v248, v35, v239
	v_mul_f32_e32 v249, v39, v239
	v_fma_f32 v243, v39, v238, -v248
	v_fma_f32 v247, v35, v238, v249
	v_mov_b64_e32 v[36:37], 0
	v_mov_b64_e32 v[38:39], 0
	v_mov_b64_e32 v[32:33], 0
	v_mov_b64_e32 v[34:35], 0
	v_cvt_pk_bf16_f32 v204, v240, v241
	v_cvt_pk_bf16_f32 v205, v242, v243
	v_cvt_pk_bf16_f32 v206, v244, v245
	v_cvt_pk_bf16_f32 v207, v246, v247
	s_nop 1
	v_permlane16_swap_b32_e32 v204, v206
	v_permlane16_swap_b32_e32 v205, v207
	global_store_dwordx4 v216, v[204:207], s[98:99]
	s_branch .Lrp_end0
; __device__ __forceinline__ unsigned cvt_pk_bf16(float lo, float hi) { unsigned r; asm volatile("v_cvt_pk_bf16_f32 %0, %1, %2" : "=v"(r) : "v"(lo), "v"(hi)); return r; }
; __device__ __forceinline__ void epi_store(const f32x4 (&acc)[2][2][4][2], const Unit& u, int wr, int wc, int fr, int fq, const EpiP& e) {
;     ...
;             for (int m = 0; m < 4; ++m) {
;                 const int row = row0 + ai * HALF + m * 16;
;                 f32x4 v0 = acc[ai][bj][m][0], v1 = acc[ai][bj][m][1];
;                 if (kind != 0 && row < MLAT) {
;                     const int t = row & (SEQ - 1); const int pos = (kind == 1) ? (t >> 6) : (t & 63);
;                     const f32x4 t0 = *(const f32x4*)(e.rope + (pos * 16 + 4 * fq) * 2), t1 = *(const f32x4*)(e.rope + (pos * 16 + 4 * fq) * 2 + 4);
;                     const float cs[4] = {t0[0], t0[2], t1[0], t1[2]}, sn[4] = {t0[1], t0[3], t1[1], t1[3]};
; #pragma unroll
;                     for (int j = 0; j < 4; ++j) { const float x1 = v0[j], x2 = v1[j]; v0[j] = x1 * cs[j] - x2 * sn[j]; v1[j] = x2 * cs[j] + x1 * sn[j]; }
;                 }
;                 bf16_t* rowp = e.O + (size_t)row * e.ldo + c;
;                 u32x2 w0, w1; w0.x = cvt_pk_bf16(v0[0], v0[1]); w0.y = cvt_pk_bf16(v0[2], v0[3]); w1.x = cvt_pk_bf16(v1[0], v1[1]); w1.y = cvt_pk_bf16(v1[2], v1[3]);
;                 const bool odd = (fq & 1) != 0;
;                 const unsigned sx = odd ? w0.x : w1.x, sy = odd ? w0.y : w1.y;
;                 const unsigned rx = (unsigned)__shfl_xor((int)sx, 16), ry = (unsigned)__shfl_xor((int)sy, 16);
;                 u32x4 w; if (odd) { w.x = rx; w.y = ry; w.z = w1.x; w.w = w1.y; } else { w.x = w0.x; w.y = w0.y; w.z = rx; w.w = ry; }
;                 *(u32x4*)(rowp + (odd ? 12 : 0)) = w;
; __device__ __forceinline__ void gemm_phase(LAS unsigned char* lds, const GemmP g, const EpiP e) {
;     ...
; #pragma unroll
;         for (int a = 0; a < 2; ++a)
; #pragma unroll
;             for (int b = 0; b < 2; ++b)
; #pragma unroll
;                 for (int m = 0; m < 4; ++m)
; #pragma unroll
;                     for (int n = 0; n < 2; ++n) acc[a][b][m][n] = (f32x4){0.f, 0.f, 0.f, 0.f};
.Lrp_plain0:
	s_mov_b64 s[98:99], s[100:101]
	v_cvt_pk_bf16_f32 v132, v128, v129
	v_cvt_pk_bf16_f32 v133, v130, v131
	v_cvt_pk_bf16_f32 v134, v124, v125
	v_cvt_pk_bf16_f32 v135, v126, v127
	v_mov_b64_e32 v[128:129], 0
	v_mov_b64_e32 v[130:131], 0
	v_mov_b64_e32 v[124:125], 0
	v_mov_b64_e32 v[126:127], 0
	s_nop 1
	v_permlane16_swap_b32_e32 v132, v134
	v_permlane16_swap_b32_e32 v133, v135
	global_store_dwordx4 v216, v[132:135], s[98:99]
	s_mul_i32 s18, s19, 1
	s_add_u32 s98, s100, s18
	s_addc_u32 s99, s101, 0
	v_cvt_pk_bf16_f32 v136, v120, v121
	v_cvt_pk_bf16_f32 v137, v122, v123
	v_cvt_pk_bf16_f32 v138, v116, v117
	v_cvt_pk_bf16_f32 v139, v118, v119
	v_mov_b64_e32 v[120:121], 0
	v_mov_b64_e32 v[122:123], 0
	v_mov_b64_e32 v[116:117], 0
	v_mov_b64_e32 v[118:119], 0
	s_nop 1
	v_permlane16_swap_b32_e32 v136, v138
	v_permlane16_swap_b32_e32 v137, v139
	global_store_dwordx4 v216, v[136:139], s[98:99]
	s_mul_i32 s18, s19, 2
	s_add_u32 s98, s100, s18
	s_addc_u32 s99, s101, 0
	v_cvt_pk_bf16_f32 v204, v112, v113
	v_cvt_pk_bf16_f32 v205, v114, v115
	v_cvt_pk_bf16_f32 v206, v108, v109
	v_cvt_pk_bf16_f32 v207, v110, v111
	v_mov_b64_e32 v[112:113], 0
	v_mov_b64_e32 v[114:115], 0
	v_mov_b64_e32 v[108:109], 0
	v_mov_b64_e32 v[110:111], 0
	s_nop 1
	v_permlane16_swap_b32_e32 v204, v206
	v_permlane16_swap_b32_e32 v205, v207
	global_store_dwordx4 v216, v[204:207], s[98:99]
	s_mul_i32 s18, s19, 3
	s_add_u32 s98, s100, s18
	s_addc_u32 s99, s101, 0
	v_cvt_pk_bf16_f32 v132, v104, v105
	v_cvt_pk_bf16_f32 v133, v106, v107
	v_cvt_pk_bf16_f32 v134, v100, v101
	v_cvt_pk_bf16_f32 v135, v102, v103
	v_mov_b64_e32 v[104:105], 0
	v_mov_b64_e32 v[106:107], 0
	v_mov_b64_e32 v[100:101], 0
	v_mov_b64_e32 v[102:103], 0
	s_nop 1
	v_permlane16_swap_b32_e32 v132, v134
	v_permlane16_swap_b32_e32 v133, v135
	global_store_dwordx4 v216, v[132:135], s[98:99]
	s_mul_i32 s18, s19, 8
	s_add_u32 s98, s100, s18
	s_addc_u32 s99, s101, 0
	v_cvt_pk_bf16_f32 v136, v60, v61
	v_cvt_pk_bf16_f32 v137, v62, v63
	v_cvt_pk_bf16_f32 v138, v56, v57
	v_cvt_pk_bf16_f32 v139, v58, v59
	v_mov_b64_e32 v[60:61], 0
	v_mov_b64_e32 v[62:63], 0
	v_mov_b64_e32 v[56:57], 0
	v_mov_b64_e32 v[58:59], 0
	s_nop 1
	v_permlane16_swap_b32_e32 v136, v138
	v_permlane16_swap_b32_e32 v137, v139
	global_store_dwordx4 v216, v[136:139], s[98:99]
	s_mul_i32 s18, s19, 9
	s_add_u32 s98, s100, s18
	s_addc_u32 s99, s101, 0
	v_cvt_pk_bf16_f32 v204, v52, v53
	v_cvt_pk_bf16_f32 v205, v54, v55
	v_cvt_pk_bf16_f32 v206, v48, v49
	v_cvt_pk_bf16_f32 v207, v50, v51
	v_mov_b64_e32 v[52:53], 0
	v_mov_b64_e32 v[54:55], 0
	v_mov_b64_e32 v[48:49], 0
	v_mov_b64_e32 v[50:51], 0
	s_nop 1
	v_permlane16_swap_b32_e32 v204, v206
	v_permlane16_swap_b32_e32 v205, v207
	global_store_dwordx4 v216, v[204:207], s[98:99]
	s_mul_i32 s18, s19, 10
	s_add_u32 s98, s100, s18
	s_addc_u32 s99, s101, 0
	v_cvt_pk_bf16_f32 v132, v44, v45
	v_cvt_pk_bf16_f32 v133, v46, v47
	v_cvt_pk_bf16_f32 v134, v40, v41
	v_cvt_pk_bf16_f32 v135, v42, v43
	v_mov_b64_e32 v[44:45], 0
	v_mov_b64_e32 v[46:47], 0
	v_mov_b64_e32 v[40:41], 0
	v_mov_b64_e32 v[42:43], 0
	s_nop 1
	v_permlane16_swap_b32_e32 v132, v134
	v_permlane16_swap_b32_e32 v133, v135
	global_store_dwordx4 v216, v[132:135], s[98:99]
	s_mul_i32 s18, s19, 11
	s_add_u32 s98, s100, s18
	s_addc_u32 s99, s101, 0
	v_cvt_pk_bf16_f32 v136, v36, v37
	v_cvt_pk_bf16_f32 v137, v38, v39
	v_cvt_pk_bf16_f32 v138, v32, v33
	v_cvt_pk_bf16_f32 v139, v34, v35
	v_mov_b64_e32 v[36:37], 0
	v_mov_b64_e32 v[38:39], 0
	v_mov_b64_e32 v[32:33], 0
	v_mov_b64_e32 v[34:35], 0
	s_nop 1
	v_permlane16_swap_b32_e32 v136, v138
	v_permlane16_swap_b32_e32 v137, v139
	global_store_dwordx4 v216, v[136:139], s[98:99]
.Lrp_end0:
	s_cmp_eq_u32 s21, 0
	s_cbranch_scc1 .Lrp_plain1
	s_cmp_eq_u32 s21, 1
	s_cbranch_scc0 .Lrp_k2_1
	s_mov_b64 s[98:99], s[100:101]
	v_mul_f32_e32 v248, v88, v161
	v_mul_f32_e32 v249, v92, v161
	v_fma_f32 v240, v92, v160, -v248
	v_fma_f32 v244, v88, v160, v249
	v_mul_f32_e32 v248, v89, v163
	v_mul_f32_e32 v249, v93, v163
	v_fma_f32 v241, v93, v162, -v248
	v_fma_f32 v245, v89, v162, v249
	v_mul_f32_e32 v248, v90, v165
	v_mul_f32_e32 v249, v94, v165
	v_fma_f32 v242, v94, v164, -v248
	v_fma_f32 v246, v90, v164, v249
	v_mul_f32_e32 v248, v91, v167
	v_mul_f32_e32 v249, v95, v167
	v_fma_f32 v243, v95, v166, -v248
	v_fma_f32 v247, v91, v166, v249
	v_mov_b64_e32 v[92:93], 0
	v_mov_b64_e32 v[94:95], 0
	v_mov_b64_e32 v[88:89], 0
	v_mov_b64_e32 v[90:91], 0
	v_cvt_pk_bf16_f32 v204, v240, v241
	v_cvt_pk_bf16_f32 v205, v242, v243
	v_cvt_pk_bf16_f32 v206, v244, v245
	v_cvt_pk_bf16_f32 v207, v246, v247
	s_nop 1
	v_permlane16_swap_b32_e32 v204, v206
	v_permlane16_swap_b32_e32 v205, v207
	global_store_dwordx4 v216, v[204:207], s[98:99] offset:256
	s_mul_i32 s18, s19, 1
	s_add_u32 s98, s100, s18
	s_addc_u32 s99, s101, 0
	v_mul_f32_e32 v248, v80, v161
	v_mul_f32_e32 v249, v84, v161
	v_fma_f32 v240, v84, v160, -v248
	v_fma_f32 v244, v80, v160, v249
	v_mul_f32_e32 v248, v81, v163
	v_mul_f32_e32 v249, v85, v163
	v_fma_f32 v241, v85, v162, -v248
	v_fma_f32 v245, v81, v162, v249
	v_mul_f32_e32 v248, v82, v165
	v_mul_f32_e32 v249, v86, v165
	v_fma_f32 v242, v86, v164, -v248
	v_fma_f32 v246, v82, v164, v249
	v_mul_f32_e32 v248, v83, v167
	v_mul_f32_e32 v249, v87, v167
	v_fma_f32 v243, v87, v166, -v248
	v_fma_f32 v247, v83, v166, v249
	v_mov_b64_e32 v[84:85], 0
	v_mov_b64_e32 v[86:87], 0
	v_mov_b64_e32 v[80:81], 0
	v_mov_b64_e32 v[82:83], 0
	v_cvt_pk_bf16_f32 v132, v240, v241
	v_cvt_pk_bf16_f32 v133, v242, v243
	v_cvt_pk_bf16_f32 v134, v244, v245
	v_cvt_pk_bf16_f32 v135, v246, v247
	s_nop 1
	v_permlane16_swap_b32_e32 v132, v134
	v_permlane16_swap_b32_e32 v133, v135
; __device__ __forceinline__ unsigned cvt_pk_bf16(float lo, float hi) { unsigned r; asm volatile("v_cvt_pk_bf16_f32 %0, %1, %2" : "=v"(r) : "v"(lo), "v"(hi)); return r; }
; __device__ __forceinline__ void epi_store(const f32x4 (&acc)[2][2][4][2], const Unit& u, int wr, int wc, int fr, int fq, const EpiP& e) {
;     ...
;             for (int m = 0; m < 4; ++m) {
;                 const int row = row0 + ai * HALF + m * 16;
;                 f32x4 v0 = acc[ai][bj][m][0], v1 = acc[ai][bj][m][1];
;                 if (kind != 0 && row < MLAT) {
;                     const int t = row & (SEQ - 1); const int pos = (kind == 1) ? (t >> 6) : (t & 63);
;                     const f32x4 t0 = *(const f32x4*)(e.rope + (pos * 16 + 4 * fq) * 2), t1 = *(const f32x4*)(e.rope + (pos * 16 + 4 * fq) * 2 + 4);
;                     const float cs[4] = {t0[0], t0[2], t1[0], t1[2]}, sn[4] = {t0[1], t0[3], t1[1], t1[3]};
; #pragma unroll
;                     for (int j = 0; j < 4; ++j) { const float x1 = v0[j], x2 = v1[j]; v0[j] = x1 * cs[j] - x2 * sn[j]; v1[j] = x2 * cs[j] + x1 * sn[j]; }
;                 }
;                 bf16_t* rowp = e.O + (size_t)row * e.ldo + c;
;                 u32x2 w0, w1; w0.x = cvt_pk_bf16(v0[0], v0[1]); w0.y = cvt_pk_bf16(v0[2], v0[3]); w1.x = cvt_pk_bf16(v1[0], v1[1]); w1.y = cvt_pk_bf16(v1[2], v1[3]);
;                 const bool odd = (fq & 1) != 0;
;                 const unsigned sx = odd ? w0.x : w1.x, sy = odd ? w0.y : w1.y;
;                 const unsigned rx = (unsigned)__shfl_xor((int)sx, 16), ry = (unsigned)__shfl_xor((int)sy, 16);
;                 u32x4 w; if (odd) { w.x = rx; w.y = ry; w.z = w1.x; w.w = w1.y; } else { w.x = w0.x; w.y = w0.y; w.z = rx; w.w = ry; }
;                 *(u32x4*)(rowp + (odd ? 12 : 0)) = w;
; __device__ __forceinline__ void gemm_phase(LAS unsigned char* lds, const GemmP g, const EpiP e) {
;     ...
; #pragma unroll
;         for (int a = 0; a < 2; ++a)
; #pragma unroll
;             for (int b = 0; b < 2; ++b)
; #pragma unroll
;                 for (int m = 0; m < 4; ++m)
; #pragma unroll
;                     for (int n = 0; n < 2; ++n) acc[a][b][m][n] = (f32x4){0.f, 0.f, 0.f, 0.f};
	global_store_dwordx4 v216, v[132:135], s[98:99] offset:256
	s_mul_i32 s18, s19, 2
	s_add_u32 s98, s100, s18
	s_addc_u32 s99, s101, 0
	v_mul_f32_e32 v248, v72, v161
	v_mul_f32_e32 v249, v76, v161
	v_fma_f32 v240, v76, v160, -v248
	v_fma_f32 v244, v72, v160, v249
	v_mul_f32_e32 v248, v73, v163
	v_mul_f32_e32 v249, v77, v163
	v_fma_f32 v241, v77, v162, -v248
	v_fma_f32 v245, v73, v162, v249
	v_mul_f32_e32 v248, v74, v165
	v_mul_f32_e32 v249, v78, v165
	v_fma_f32 v242, v78, v164, -v248
	v_fma_f32 v246, v74, v164, v249
	v_mul_f32_e32 v248, v75, v167
	v_mul_f32_e32 v249, v79, v167
	v_fma_f32 v243, v79, v166, -v248
	v_fma_f32 v247, v75, v166, v249
	v_mov_b64_e32 v[76:77], 0
	v_mov_b64_e32 v[78:79], 0
	v_mov_b64_e32 v[72:73], 0
	v_mov_b64_e32 v[74:75], 0
	v_cvt_pk_bf16_f32 v136, v240, v241
	v_cvt_pk_bf16_f32 v137, v242, v243
	v_cvt_pk_bf16_f32 v138, v244, v245
	v_cvt_pk_bf16_f32 v139, v246, v247
	s_nop 1
	v_permlane16_swap_b32_e32 v136, v138
	v_permlane16_swap_b32_e32 v137, v139
	global_store_dwordx4 v216, v[136:139], s[98:99] offset:256
	s_mul_i32 s18, s19, 3
	s_add_u32 s98, s100, s18
	s_addc_u32 s99, s101, 0
	v_mul_f32_e32 v248, v64, v161
	v_mul_f32_e32 v249, v68, v161
	v_fma_f32 v240, v68, v160, -v248
	v_fma_f32 v244, v64, v160, v249
	v_mul_f32_e32 v248, v65, v163
	v_mul_f32_e32 v249, v69, v163
	v_fma_f32 v241, v69, v162, -v248
	v_fma_f32 v245, v65, v162, v249
	v_mul_f32_e32 v248, v66, v165
	v_mul_f32_e32 v249, v70, v165
	v_fma_f32 v242, v70, v164, -v248
	v_fma_f32 v246, v66, v164, v249
	v_mul_f32_e32 v248, v67, v167
	v_mul_f32_e32 v249, v71, v167
	v_fma_f32 v243, v71, v166, -v248
	v_fma_f32 v247, v67, v166, v249
	v_mov_b64_e32 v[68:69], 0
	v_mov_b64_e32 v[70:71], 0
	v_mov_b64_e32 v[64:65], 0
	v_mov_b64_e32 v[66:67], 0
	v_cvt_pk_bf16_f32 v204, v240, v241
	v_cvt_pk_bf16_f32 v205, v242, v243
	v_cvt_pk_bf16_f32 v206, v244, v245
	v_cvt_pk_bf16_f32 v207, v246, v247
	s_nop 1
	v_permlane16_swap_b32_e32 v204, v206
	v_permlane16_swap_b32_e32 v205, v207
	global_store_dwordx4 v216, v[204:207], s[98:99] offset:256
	s_mul_i32 s18, s19, 8
	s_add_u32 s98, s100, s18
	s_addc_u32 s99, s101, 0
	v_mul_f32_e32 v248, v24, v169
	v_mul_f32_e32 v249, v28, v169
	v_fma_f32 v240, v28, v168, -v248
	v_fma_f32 v244, v24, v168, v249
	v_mul_f32_e32 v248, v25, v171
	v_mul_f32_e32 v249, v29, v171
	v_fma_f32 v241, v29, v170, -v248
	v_fma_f32 v245, v25, v170, v249
	v_mul_f32_e32 v248, v26, v173
	v_mul_f32_e32 v249, v30, v173
	v_fma_f32 v242, v30, v172, -v248
	v_fma_f32 v246, v26, v172, v249
	v_mul_f32_e32 v248, v27, v175
	v_mul_f32_e32 v249, v31, v175
	v_fma_f32 v243, v31, v174, -v248
	v_fma_f32 v247, v27, v174, v249
	v_mov_b64_e32 v[28:29], 0
	v_mov_b64_e32 v[30:31], 0
	v_mov_b64_e32 v[24:25], 0
	v_mov_b64_e32 v[26:27], 0
	v_cvt_pk_bf16_f32 v132, v240, v241
	v_cvt_pk_bf16_f32 v133, v242, v243
	v_cvt_pk_bf16_f32 v134, v244, v245
	v_cvt_pk_bf16_f32 v135, v246, v247
	s_nop 1
	v_permlane16_swap_b32_e32 v132, v134
	v_permlane16_swap_b32_e32 v133, v135
	global_store_dwordx4 v216, v[132:135], s[98:99] offset:256
	s_mul_i32 s18, s19, 9
	s_add_u32 s98, s100, s18
	s_addc_u32 s99, s101, 0
	v_mul_f32_e32 v248, v16, v169
	v_mul_f32_e32 v249, v20, v169
	v_fma_f32 v240, v20, v168, -v248
	v_fma_f32 v244, v16, v168, v249
	v_mul_f32_e32 v248, v17, v171
	v_mul_f32_e32 v249, v21, v171
	v_fma_f32 v241, v21, v170, -v248
	v_fma_f32 v245, v17, v170, v249
	v_mul_f32_e32 v248, v18, v173
	v_mul_f32_e32 v249, v22, v173
	v_fma_f32 v242, v22, v172, -v248
	v_fma_f32 v246, v18, v172, v249
	v_mul_f32_e32 v248, v19, v175
	v_mul_f32_e32 v249, v23, v175
	v_fma_f32 v243, v23, v174, -v248
	v_fma_f32 v247, v19, v174, v249
	v_mov_b64_e32 v[20:21], 0
	v_mov_b64_e32 v[22:23], 0
	v_mov_b64_e32 v[16:17], 0
	v_mov_b64_e32 v[18:19], 0
	v_cvt_pk_bf16_f32 v136, v240, v241
	v_cvt_pk_bf16_f32 v137, v242, v243
	v_cvt_pk_bf16_f32 v138, v244, v245
	v_cvt_pk_bf16_f32 v139, v246, v247
	s_nop 1
	v_permlane16_swap_b32_e32 v136, v138
	v_permlane16_swap_b32_e32 v137, v139
	global_store_dwordx4 v216, v[136:139], s[98:99] offset:256
	s_mul_i32 s18, s19, 10
	s_add_u32 s98, s100, s18
	s_addc_u32 s99, s101, 0
	v_mul_f32_e32 v248, v8, v169
	v_mul_f32_e32 v249, v12, v169
	v_fma_f32 v240, v12, v168, -v248
	v_fma_f32 v244, v8, v168, v249
	v_mul_f32_e32 v248, v9, v171
	v_mul_f32_e32 v249, v13, v171
	v_fma_f32 v241, v13, v170, -v248
	v_fma_f32 v245, v9, v170, v249
	v_mul_f32_e32 v248, v10, v173
	v_mul_f32_e32 v249, v14, v173
	v_fma_f32 v242, v14, v172, -v248
	v_fma_f32 v246, v10, v172, v249
	v_mul_f32_e32 v248, v11, v175
	v_mul_f32_e32 v249, v15, v175
	v_fma_f32 v243, v15, v174, -v248
	v_fma_f32 v247, v11, v174, v249
	v_mov_b64_e32 v[12:13], 0
	v_mov_b64_e32 v[14:15], 0
	v_mov_b64_e32 v[8:9], 0
	v_mov_b64_e32 v[10:11], 0
	v_cvt_pk_bf16_f32 v204, v240, v241
	v_cvt_pk_bf16_f32 v205, v242, v243
	v_cvt_pk_bf16_f32 v206, v244, v245
	v_cvt_pk_bf16_f32 v207, v246, v247
	s_nop 1
	v_permlane16_swap_b32_e32 v204, v206
	v_permlane16_swap_b32_e32 v205, v207
	global_store_dwordx4 v216, v[204:207], s[98:99] offset:256
	s_mul_i32 s18, s19, 11
	s_add_u32 s98, s100, s18
	s_addc_u32 s99, s101, 0
	v_mul_f32_e32 v248, v0, v169
	v_mul_f32_e32 v249, v4, v169
	v_fma_f32 v240, v4, v168, -v248
	v_fma_f32 v244, v0, v168, v249
	v_mul_f32_e32 v248, v1, v171
	v_mul_f32_e32 v249, v5, v171
	v_fma_f32 v241, v5, v170, -v248
	v_fma_f32 v245, v1, v170, v249
	v_mul_f32_e32 v248, v2, v173
	v_mul_f32_e32 v249, v6, v173
	v_fma_f32 v242, v6, v172, -v248
	v_fma_f32 v246, v2, v172, v249
	v_mul_f32_e32 v248, v3, v175
	v_mul_f32_e32 v249, v7, v175
	v_fma_f32 v243, v7, v174, -v248
	v_fma_f32 v247, v3, v174, v249
	v_mov_b64_e32 v[4:5], 0
	v_mov_b64_e32 v[6:7], 0
	v_mov_b64_e32 v[0:1], 0
	v_mov_b64_e32 v[2:3], 0
	v_cvt_pk_bf16_f32 v132, v240, v241
	v_cvt_pk_bf16_f32 v133, v242, v243
	v_cvt_pk_bf16_f32 v134, v244, v245
	v_cvt_pk_bf16_f32 v135, v246, v247
	s_nop 1
	v_permlane16_swap_b32_e32 v132, v134
	v_permlane16_swap_b32_e32 v133, v135
	global_store_dwordx4 v216, v[132:135], s[98:99] offset:256
	s_branch .Lrp_end1
; __device__ __forceinline__ unsigned cvt_pk_bf16(float lo, float hi) { unsigned r; asm volatile("v_cvt_pk_bf16_f32 %0, %1, %2" : "=v"(r) : "v"(lo), "v"(hi)); return r; }
; __device__ __forceinline__ void epi_store(const f32x4 (&acc)[2][2][4][2], const Unit& u, int wr, int wc, int fr, int fq, const EpiP& e) {
;     ...
;             for (int m = 0; m < 4; ++m) {
;                 const int row = row0 + ai * HALF + m * 16;
;                 f32x4 v0 = acc[ai][bj][m][0], v1 = acc[ai][bj][m][1];
;                 if (kind != 0 && row < MLAT) {
;                     const int t = row & (SEQ - 1); const int pos = (kind == 1) ? (t >> 6) : (t & 63);
;                     const f32x4 t0 = *(const f32x4*)(e.rope + (pos * 16 + 4 * fq) * 2), t1 = *(const f32x4*)(e.rope + (pos * 16 + 4 * fq) * 2 + 4);
;                     const float cs[4] = {t0[0], t0[2], t1[0], t1[2]}, sn[4] = {t0[1], t0[3], t1[1], t1[3]};
; #pragma unroll
;                     for (int j = 0; j < 4; ++j) { const float x1 = v0[j], x2 = v1[j]; v0[j] = x1 * cs[j] - x2 * sn[j]; v1[j] = x2 * cs[j] + x1 * sn[j]; }
;                 }
;                 bf16_t* rowp = e.O + (size_t)row * e.ldo + c;
;                 u32x2 w0, w1; w0.x = cvt_pk_bf16(v0[0], v0[1]); w0.y = cvt_pk_bf16(v0[2], v0[3]); w1.x = cvt_pk_bf16(v1[0], v1[1]); w1.y = cvt_pk_bf16(v1[2], v1[3]);
;                 const bool odd = (fq & 1) != 0;
;                 const unsigned sx = odd ? w0.x : w1.x, sy = odd ? w0.y : w1.y;
;                 const unsigned rx = (unsigned)__shfl_xor((int)sx, 16), ry = (unsigned)__shfl_xor((int)sy, 16);
;                 u32x4 w; if (odd) { w.x = rx; w.y = ry; w.z = w1.x; w.w = w1.y; } else { w.x = w0.x; w.y = w0.y; w.z = rx; w.w = ry; }
;                 *(u32x4*)(rowp + (odd ? 12 : 0)) = w;
; __device__ __forceinline__ void gemm_phase(LAS unsigned char* lds, const GemmP g, const EpiP e) {
;     ...
; #pragma unroll
;         for (int a = 0; a < 2; ++a)
; #pragma unroll
;             for (int b = 0; b < 2; ++b)
; #pragma unroll
;                 for (int m = 0; m < 4; ++m)
; #pragma unroll
;                     for (int n = 0; n < 2; ++n) acc[a][b][m][n] = (f32x4){0.f, 0.f, 0.f, 0.f};
.Lrp_k2_1:
	s_mov_b64 s[98:99], s[100:101]
	v_mul_f32_e32 v248, v88, v161
	v_mul_f32_e32 v249, v92, v161
	v_fma_f32 v240, v92, v160, -v248
	v_fma_f32 v244, v88, v160, v249
	v_mul_f32_e32 v248, v89, v163
	v_mul_f32_e32 v249, v93, v163
	v_fma_f32 v241, v93, v162, -v248
	v_fma_f32 v245, v89, v162, v249
	v_mul_f32_e32 v248, v90, v165
	v_mul_f32_e32 v249, v94, v165
	v_fma_f32 v242, v94, v164, -v248
	v_fma_f32 v246, v90, v164, v249
	v_mul_f32_e32 v248, v91, v167
	v_mul_f32_e32 v249, v95, v167
	v_fma_f32 v243, v95, v166, -v248
	v_fma_f32 v247, v91, v166, v249
	v_mov_b64_e32 v[92:93], 0
	v_mov_b64_e32 v[94:95], 0
	v_mov_b64_e32 v[88:89], 0
	v_mov_b64_e32 v[90:91], 0
	v_cvt_pk_bf16_f32 v136, v240, v241
	v_cvt_pk_bf16_f32 v137, v242, v243
	v_cvt_pk_bf16_f32 v138, v244, v245
	v_cvt_pk_bf16_f32 v139, v246, v247
	s_nop 1
	v_permlane16_swap_b32_e32 v136, v138
	v_permlane16_swap_b32_e32 v137, v139
	global_store_dwordx4 v216, v[136:139], s[98:99] offset:256
	s_mul_i32 s18, s19, 1
	s_add_u32 s98, s100, s18
	s_addc_u32 s99, s101, 0
	v_mul_f32_e32 v248, v80, v169
	v_mul_f32_e32 v249, v84, v169
	v_fma_f32 v240, v84, v168, -v248
	v_fma_f32 v244, v80, v168, v249
	v_mul_f32_e32 v248, v81, v171
	v_mul_f32_e32 v249, v85, v171
	v_fma_f32 v241, v85, v170, -v248
	v_fma_f32 v245, v81, v170, v249
	v_mul_f32_e32 v248, v82, v173
	v_mul_f32_e32 v249, v86, v173
	v_fma_f32 v242, v86, v172, -v248
	v_fma_f32 v246, v82, v172, v249
	v_mul_f32_e32 v248, v83, v175
	v_mul_f32_e32 v249, v87, v175
	v_fma_f32 v243, v87, v174, -v248
	v_fma_f32 v247, v83, v174, v249
	v_mov_b64_e32 v[84:85], 0
	v_mov_b64_e32 v[86:87], 0
	v_mov_b64_e32 v[80:81], 0
	v_mov_b64_e32 v[82:83], 0
	v_cvt_pk_bf16_f32 v204, v240, v241
	v_cvt_pk_bf16_f32 v205, v242, v243
	v_cvt_pk_bf16_f32 v206, v244, v245
	v_cvt_pk_bf16_f32 v207, v246, v247
	s_nop 1
	v_permlane16_swap_b32_e32 v204, v206
	v_permlane16_swap_b32_e32 v205, v207
	global_store_dwordx4 v216, v[204:207], s[98:99] offset:256
	s_mul_i32 s18, s19, 2
	s_add_u32 s98, s100, s18
	s_addc_u32 s99, s101, 0
	v_mul_f32_e32 v248, v72, v225
	v_mul_f32_e32 v249, v76, v225
	v_fma_f32 v240, v76, v224, -v248
	v_fma_f32 v244, v72, v224, v249
	v_mul_f32_e32 v248, v73, v227
	v_mul_f32_e32 v249, v77, v227
	v_fma_f32 v241, v77, v226, -v248
	v_fma_f32 v245, v73, v226, v249
	v_mul_f32_e32 v248, v74, v229
	v_mul_f32_e32 v249, v78, v229
	v_fma_f32 v242, v78, v228, -v248
	v_fma_f32 v246, v74, v228, v249
	v_mul_f32_e32 v248, v75, v231
	v_mul_f32_e32 v249, v79, v231
	v_fma_f32 v243, v79, v230, -v248
	v_fma_f32 v247, v75, v230, v249
	v_mov_b64_e32 v[76:77], 0
	v_mov_b64_e32 v[78:79], 0
	v_mov_b64_e32 v[72:73], 0
	v_mov_b64_e32 v[74:75], 0
	v_cvt_pk_bf16_f32 v132, v240, v241
	v_cvt_pk_bf16_f32 v133, v242, v243
	v_cvt_pk_bf16_f32 v134, v244, v245
	v_cvt_pk_bf16_f32 v135, v246, v247
	s_nop 1
	v_permlane16_swap_b32_e32 v132, v134
	v_permlane16_swap_b32_e32 v133, v135
	global_store_dwordx4 v216, v[132:135], s[98:99] offset:256
	s_mul_i32 s18, s19, 3
	s_add_u32 s98, s100, s18
	s_addc_u32 s99, s101, 0
	v_mul_f32_e32 v248, v64, v233
	v_mul_f32_e32 v249, v68, v233
	v_fma_f32 v240, v68, v232, -v248
	v_fma_f32 v244, v64, v232, v249
	v_mul_f32_e32 v248, v65, v235
	v_mul_f32_e32 v249, v69, v235
	v_fma_f32 v241, v69, v234, -v248
	v_fma_f32 v245, v65, v234, v249
	v_mul_f32_e32 v248, v66, v237
	v_mul_f32_e32 v249, v70, v237
	v_fma_f32 v242, v70, v236, -v248
	v_fma_f32 v246, v66, v236, v249
	v_mul_f32_e32 v248, v67, v239
	v_mul_f32_e32 v249, v71, v239
	v_fma_f32 v243, v71, v238, -v248
	v_fma_f32 v247, v67, v238, v249
	v_mov_b64_e32 v[68:69], 0
	v_mov_b64_e32 v[70:71], 0
	v_mov_b64_e32 v[64:65], 0
	v_mov_b64_e32 v[66:67], 0
	v_cvt_pk_bf16_f32 v136, v240, v241
	v_cvt_pk_bf16_f32 v137, v242, v243
	v_cvt_pk_bf16_f32 v138, v244, v245
	v_cvt_pk_bf16_f32 v139, v246, v247
	s_nop 1
	v_permlane16_swap_b32_e32 v136, v138
	v_permlane16_swap_b32_e32 v137, v139
	global_store_dwordx4 v216, v[136:139], s[98:99] offset:256
	s_mul_i32 s18, s19, 8
	s_add_u32 s98, s100, s18
	s_addc_u32 s99, s101, 0
	v_mul_f32_e32 v248, v24, v161
	v_mul_f32_e32 v249, v28, v161
	v_fma_f32 v240, v28, v160, -v248
	v_fma_f32 v244, v24, v160, v249
	v_mul_f32_e32 v248, v25, v163
	v_mul_f32_e32 v249, v29, v163
	v_fma_f32 v241, v29, v162, -v248
	v_fma_f32 v245, v25, v162, v249
	v_mul_f32_e32 v248, v26, v165
	v_mul_f32_e32 v249, v30, v165
	v_fma_f32 v242, v30, v164, -v248
	v_fma_f32 v246, v26, v164, v249
	v_mul_f32_e32 v248, v27, v167
	v_mul_f32_e32 v249, v31, v167
	v_fma_f32 v243, v31, v166, -v248
	v_fma_f32 v247, v27, v166, v249
	v_mov_b64_e32 v[28:29], 0
	v_mov_b64_e32 v[30:31], 0
	v_mov_b64_e32 v[24:25], 0
	v_mov_b64_e32 v[26:27], 0
	v_cvt_pk_bf16_f32 v204, v240, v241
	v_cvt_pk_bf16_f32 v205, v242, v243
	v_cvt_pk_bf16_f32 v206, v244, v245
	v_cvt_pk_bf16_f32 v207, v246, v247
	s_nop 1
	v_permlane16_swap_b32_e32 v204, v206
	v_permlane16_swap_b32_e32 v205, v207
	global_store_dwordx4 v216, v[204:207], s[98:99] offset:256
	s_mul_i32 s18, s19, 9
	s_add_u32 s98, s100, s18
	s_addc_u32 s99, s101, 0
	v_mul_f32_e32 v248, v16, v169
	v_mul_f32_e32 v249, v20, v169
	v_fma_f32 v240, v20, v168, -v248
	v_fma_f32 v244, v16, v168, v249
	v_mul_f32_e32 v248, v17, v171
	v_mul_f32_e32 v249, v21, v171
	v_fma_f32 v241, v21, v170, -v248
	v_fma_f32 v245, v17, v170, v249
	v_mul_f32_e32 v248, v18, v173
	v_mul_f32_e32 v249, v22, v173
	v_fma_f32 v242, v22, v172, -v248
	v_fma_f32 v246, v18, v172, v249
	v_mul_f32_e32 v248, v19, v175
	v_mul_f32_e32 v249, v23, v175
	v_fma_f32 v243, v23, v174, -v248
	v_fma_f32 v247, v19, v174, v249
	v_mov_b64_e32 v[20:21], 0
	v_mov_b64_e32 v[22:23], 0
	v_mov_b64_e32 v[16:17], 0
	v_mov_b64_e32 v[18:19], 0
	v_cvt_pk_bf16_f32 v132, v240, v241
; __device__ __forceinline__ unsigned cvt_pk_bf16(float lo, float hi) { unsigned r; asm volatile("v_cvt_pk_bf16_f32 %0, %1, %2" : "=v"(r) : "v"(lo), "v"(hi)); return r; }
; __device__ __forceinline__ void epi_store(const f32x4 (&acc)[2][2][4][2], const Unit& u, int wr, int wc, int fr, int fq, const EpiP& e) {
;     ...
;             for (int m = 0; m < 4; ++m) {
;                 const int row = row0 + ai * HALF + m * 16;
;                 f32x4 v0 = acc[ai][bj][m][0], v1 = acc[ai][bj][m][1];
;                 if (kind != 0 && row < MLAT) {
;                     const int t = row & (SEQ - 1); const int pos = (kind == 1) ? (t >> 6) : (t & 63);
;                     const f32x4 t0 = *(const f32x4*)(e.rope + (pos * 16 + 4 * fq) * 2), t1 = *(const f32x4*)(e.rope + (pos * 16 + 4 * fq) * 2 + 4);
;                     const float cs[4] = {t0[0], t0[2], t1[0], t1[2]}, sn[4] = {t0[1], t0[3], t1[1], t1[3]};
; #pragma unroll
;                     for (int j = 0; j < 4; ++j) { const float x1 = v0[j], x2 = v1[j]; v0[j] = x1 * cs[j] - x2 * sn[j]; v1[j] = x2 * cs[j] + x1 * sn[j]; }
;                 }
;                 bf16_t* rowp = e.O + (size_t)row * e.ldo + c;
;                 u32x2 w0, w1; w0.x = cvt_pk_bf16(v0[0], v0[1]); w0.y = cvt_pk_bf16(v0[2], v0[3]); w1.x = cvt_pk_bf16(v1[0], v1[1]); w1.y = cvt_pk_bf16(v1[2], v1[3]);
;                 const bool odd = (fq & 1) != 0;
;                 const unsigned sx = odd ? w0.x : w1.x, sy = odd ? w0.y : w1.y;
;                 const unsigned rx = (unsigned)__shfl_xor((int)sx, 16), ry = (unsigned)__shfl_xor((int)sy, 16);
;                 u32x4 w; if (odd) { w.x = rx; w.y = ry; w.z = w1.x; w.w = w1.y; } else { w.x = w0.x; w.y = w0.y; w.z = rx; w.w = ry; }
;                 *(u32x4*)(rowp + (odd ? 12 : 0)) = w;
; __device__ __forceinline__ void gemm_phase(LAS unsigned char* lds, const GemmP g, const EpiP e) {
;     ...
; #pragma unroll
;         for (int a = 0; a < 2; ++a)
; #pragma unroll
;             for (int b = 0; b < 2; ++b)
; #pragma unroll
;                 for (int m = 0; m < 4; ++m)
; #pragma unroll
;                     for (int n = 0; n < 2; ++n) acc[a][b][m][n] = (f32x4){0.f, 0.f, 0.f, 0.f};
	v_cvt_pk_bf16_f32 v133, v242, v243
	v_cvt_pk_bf16_f32 v134, v244, v245
	v_cvt_pk_bf16_f32 v135, v246, v247
	s_nop 1
	v_permlane16_swap_b32_e32 v132, v134
	v_permlane16_swap_b32_e32 v133, v135
	global_store_dwordx4 v216, v[132:135], s[98:99] offset:256
	s_mul_i32 s18, s19, 10
	s_add_u32 s98, s100, s18
	s_addc_u32 s99, s101, 0
	v_mul_f32_e32 v248, v8, v225
	v_mul_f32_e32 v249, v12, v225
	v_fma_f32 v240, v12, v224, -v248
	v_fma_f32 v244, v8, v224, v249
	v_mul_f32_e32 v248, v9, v227
	v_mul_f32_e32 v249, v13, v227
	v_fma_f32 v241, v13, v226, -v248
	v_fma_f32 v245, v9, v226, v249
	v_mul_f32_e32 v248, v10, v229
	v_mul_f32_e32 v249, v14, v229
	v_fma_f32 v242, v14, v228, -v248
	v_fma_f32 v246, v10, v228, v249
	v_mul_f32_e32 v248, v11, v231
	v_mul_f32_e32 v249, v15, v231
	v_fma_f32 v243, v15, v230, -v248
	v_fma_f32 v247, v11, v230, v249
	v_mov_b64_e32 v[12:13], 0
	v_mov_b64_e32 v[14:15], 0
	v_mov_b64_e32 v[8:9], 0
	v_mov_b64_e32 v[10:11], 0
	v_cvt_pk_bf16_f32 v136, v240, v241
	v_cvt_pk_bf16_f32 v137, v242, v243
	v_cvt_pk_bf16_f32 v138, v244, v245
	v_cvt_pk_bf16_f32 v139, v246, v247
	s_nop 1
	v_permlane16_swap_b32_e32 v136, v138
	v_permlane16_swap_b32_e32 v137, v139
	global_store_dwordx4 v216, v[136:139], s[98:99] offset:256
	s_mul_i32 s18, s19, 11
	s_add_u32 s98, s100, s18
	s_addc_u32 s99, s101, 0
	v_mul_f32_e32 v248, v0, v233
	v_mul_f32_e32 v249, v4, v233
	v_fma_f32 v240, v4, v232, -v248
	v_fma_f32 v244, v0, v232, v249
	v_mul_f32_e32 v248, v1, v235
	v_mul_f32_e32 v249, v5, v235
	v_fma_f32 v241, v5, v234, -v248
	v_fma_f32 v245, v1, v234, v249
	v_mul_f32_e32 v248, v2, v237
	v_mul_f32_e32 v249, v6, v237
	v_fma_f32 v242, v6, v236, -v248
	v_fma_f32 v246, v2, v236, v249
	v_mul_f32_e32 v248, v3, v239
	v_mul_f32_e32 v249, v7, v239
	v_fma_f32 v243, v7, v238, -v248
	v_fma_f32 v247, v3, v238, v249
	v_mov_b64_e32 v[4:5], 0
	v_mov_b64_e32 v[6:7], 0
	v_mov_b64_e32 v[0:1], 0
	v_mov_b64_e32 v[2:3], 0
	v_cvt_pk_bf16_f32 v204, v240, v241
	v_cvt_pk_bf16_f32 v205, v242, v243
	v_cvt_pk_bf16_f32 v206, v244, v245
	v_cvt_pk_bf16_f32 v207, v246, v247
	s_nop 1
	v_permlane16_swap_b32_e32 v204, v206
	v_permlane16_swap_b32_e32 v205, v207
	global_store_dwordx4 v216, v[204:207], s[98:99] offset:256
	s_branch .Lrp_end1
.Lrp_plain1:
	s_mov_b64 s[98:99], s[100:101]
	v_cvt_pk_bf16_f32 v132, v92, v93
	v_cvt_pk_bf16_f32 v133, v94, v95
	v_cvt_pk_bf16_f32 v134, v88, v89
	v_cvt_pk_bf16_f32 v135, v90, v91
	v_mov_b64_e32 v[92:93], 0
	v_mov_b64_e32 v[94:95], 0
	v_mov_b64_e32 v[88:89], 0
	v_mov_b64_e32 v[90:91], 0
	s_nop 1
	v_permlane16_swap_b32_e32 v132, v134
	v_permlane16_swap_b32_e32 v133, v135
	global_store_dwordx4 v216, v[132:135], s[98:99] offset:256
	s_mul_i32 s18, s19, 1
	s_add_u32 s98, s100, s18
	s_addc_u32 s99, s101, 0
	v_cvt_pk_bf16_f32 v136, v84, v85
	v_cvt_pk_bf16_f32 v137, v86, v87
	v_cvt_pk_bf16_f32 v138, v80, v81
	v_cvt_pk_bf16_f32 v139, v82, v83
	v_mov_b64_e32 v[84:85], 0
	v_mov_b64_e32 v[86:87], 0
	v_mov_b64_e32 v[80:81], 0
	v_mov_b64_e32 v[82:83], 0
	s_nop 1
	v_permlane16_swap_b32_e32 v136, v138
	v_permlane16_swap_b32_e32 v137, v139
	global_store_dwordx4 v216, v[136:139], s[98:99] offset:256
	s_mul_i32 s18, s19, 2
	s_add_u32 s98, s100, s18
	s_addc_u32 s99, s101, 0
	v_cvt_pk_bf16_f32 v204, v76, v77
	v_cvt_pk_bf16_f32 v205, v78, v79
	v_cvt_pk_bf16_f32 v206, v72, v73
	v_cvt_pk_bf16_f32 v207, v74, v75
	v_mov_b64_e32 v[76:77], 0
	v_mov_b64_e32 v[78:79], 0
	v_mov_b64_e32 v[72:73], 0
	v_mov_b64_e32 v[74:75], 0
	s_nop 1
	v_permlane16_swap_b32_e32 v204, v206
	v_permlane16_swap_b32_e32 v205, v207
	global_store_dwordx4 v216, v[204:207], s[98:99] offset:256
	s_mul_i32 s18, s19, 3
	s_add_u32 s98, s100, s18
	s_addc_u32 s99, s101, 0
	v_cvt_pk_bf16_f32 v132, v68, v69
	v_cvt_pk_bf16_f32 v133, v70, v71
	v_cvt_pk_bf16_f32 v134, v64, v65
	v_cvt_pk_bf16_f32 v135, v66, v67
	v_mov_b64_e32 v[68:69], 0
	v_mov_b64_e32 v[70:71], 0
	v_mov_b64_e32 v[64:65], 0
	v_mov_b64_e32 v[66:67], 0
	s_nop 1
	v_permlane16_swap_b32_e32 v132, v134
	v_permlane16_swap_b32_e32 v133, v135
	global_store_dwordx4 v216, v[132:135], s[98:99] offset:256
	s_mul_i32 s18, s19, 8
	s_add_u32 s98, s100, s18
	s_addc_u32 s99, s101, 0
	v_cvt_pk_bf16_f32 v136, v28, v29
	v_cvt_pk_bf16_f32 v137, v30, v31
	v_cvt_pk_bf16_f32 v138, v24, v25
	v_cvt_pk_bf16_f32 v139, v26, v27
	v_mov_b64_e32 v[28:29], 0
	v_mov_b64_e32 v[30:31], 0
	v_mov_b64_e32 v[24:25], 0
	v_mov_b64_e32 v[26:27], 0
	s_nop 1
	v_permlane16_swap_b32_e32 v136, v138
	v_permlane16_swap_b32_e32 v137, v139
	global_store_dwordx4 v216, v[136:139], s[98:99] offset:256
	s_mul_i32 s18, s19, 9
	s_add_u32 s98, s100, s18
	s_addc_u32 s99, s101, 0
	v_cvt_pk_bf16_f32 v204, v20, v21
	v_cvt_pk_bf16_f32 v205, v22, v23
	v_cvt_pk_bf16_f32 v206, v16, v17
	v_cvt_pk_bf16_f32 v207, v18, v19
	v_mov_b64_e32 v[20:21], 0
	v_mov_b64_e32 v[22:23], 0
	v_mov_b64_e32 v[16:17], 0
	v_mov_b64_e32 v[18:19], 0
	s_nop 1
	v_permlane16_swap_b32_e32 v204, v206
	v_permlane16_swap_b32_e32 v205, v207
	global_store_dwordx4 v216, v[204:207], s[98:99] offset:256
	s_mul_i32 s18, s19, 10
	s_add_u32 s98, s100, s18
	s_addc_u32 s99, s101, 0
	v_cvt_pk_bf16_f32 v132, v12, v13
	v_cvt_pk_bf16_f32 v133, v14, v15
	v_cvt_pk_bf16_f32 v134, v8, v9
	v_cvt_pk_bf16_f32 v135, v10, v11
	v_mov_b64_e32 v[12:13], 0
	v_mov_b64_e32 v[14:15], 0
	v_mov_b64_e32 v[8:9], 0
	v_mov_b64_e32 v[10:11], 0
	s_nop 1
	v_permlane16_swap_b32_e32 v132, v134
	v_permlane16_swap_b32_e32 v133, v135
	global_store_dwordx4 v216, v[132:135], s[98:99] offset:256
	s_mul_i32 s18, s19, 11
	s_add_u32 s98, s100, s18
	s_addc_u32 s99, s101, 0
	v_cvt_pk_bf16_f32 v136, v4, v5
	v_cvt_pk_bf16_f32 v137, v6, v7
	v_cvt_pk_bf16_f32 v138, v0, v1
	v_cvt_pk_bf16_f32 v139, v2, v3
	v_mov_b64_e32 v[4:5], 0
	v_mov_b64_e32 v[6:7], 0
	v_mov_b64_e32 v[0:1], 0
	v_mov_b64_e32 v[2:3], 0
	s_nop 1
	v_permlane16_swap_b32_e32 v136, v138
	v_permlane16_swap_b32_e32 v137, v139
	global_store_dwordx4 v216, v[136:139], s[98:99] offset:256

; __device__ __forceinline__ unsigned cvt_pk_bf16(float lo, float hi) { unsigned r; asm volatile("v_cvt_pk_bf16_f32 %0, %1, %2" : "=v"(r) : "v"(lo), "v"(hi)); return r; }
; __device__ __forceinline__ void epi_store(const f32x4 (&acc)[2][2][4][2], const Unit& u, int wr, int wc, int fr, int fq, const EpiP& e) {
;     ...
;         const int col0 = u.pn * BM + wc * 32 + 8 * fq;
; #pragma unroll
;         for (int bj = 0; bj < 2; ++bj) {
;             const int c = col0 + bj * HALF;
;             f32x4 cs0 = {1.f, 1.f, 1.f, 1.f}, cs1 = {1.f, 1.f, 1.f, 1.f};
;             if (e.mode == 0 && e.colscale) { cs0 = *(const f32x4*)(e.colscale + c); cs1 = *(const f32x4*)(e.colscale + c + 4); }
; #pragma unroll
;             for (int ai = 0; ai < 2; ++ai)
; #pragma unroll
;                 for (int m = 0; m < 4; ++m) {
;                     const int row = row0 + ai * HALF + m * 16;
;                     f32x4 v0 = acc[ai][bj][m][0], v1 = acc[ai][bj][m][1];
;                     if (e.mode == 1) {
; #pragma unroll
;                         for (int j = 0; j < 4; ++j) { const float a = fmaxf(v0[j], 0.f), b = fmaxf(v1[j], 0.f); v0[j] = a * a; v1[j] = b * b; }
;                     } else { v0 *= cs0; v1 *= cs1; }
;                     bf16_t* rowp = (u.ks < 0 ? e.O + (size_t)row * e.ldo : e.Opart + ((size_t)u.ks * MCTX + (row - MLAT)) * 1024) + c;
;                     if (e.mode == 1)
;                         rowp = (bf16_t*)((char*)e.O + ((size_t)(u.pm * 64 + u.pn * 4 + bj * 2 + (wc >> 1))) * 32768 + ai * 16384 + (((wr * 4 + m) * 2 + (wc & 1)) * 1024) + (fr * 4 + fq) * 16);
;                     u32x4 w; w.x = cvt_pk_bf16(v0[0], v0[1]); w.y = cvt_pk_bf16(v0[2], v0[3]); w.z = cvt_pk_bf16(v1[0], v1[1]); w.w = cvt_pk_bf16(v1[2], v1[3]);
;                     *(u32x4*)rowp = w;
; __device__ __forceinline__ void gemm_phase(LAS unsigned char* lds, const GemmP g, const EpiP e) {
;     ...
; #pragma unroll
;         for (int a = 0; a < 2; ++a)
; #pragma unroll
;             for (int b = 0; b < 2; ++b)
; #pragma unroll
;                 for (int m = 0; m < 4; ++m)
; #pragma unroll
;                     for (int n = 0; n < 2; ++n) acc[a][b][m][n] = (f32x4){0.f, 0.f, 0.f, 0.f};
.Lep0_common:
	v_lshl_or_b32 v217, v218, 6, v217
	v_bfe_u32 v218, v159, 6, 2
	v_lshlrev_b32_e32 v218, 5, v218
	v_lshl_or_b32 v218, v219, 3, v218
	v_mul_lo_u32 v217, v217, s18
	v_add_lshl_u32 v216, v217, v218, 1
	s_lshl_b32 s17, s18, 5
	v_readlane_b32 s20, v255, 26
	v_readlane_b32 s21, v255, 27
	s_and_b64 vcc, exec, s[20:21]
	s_cbranch_vccnz .Lep0_cs
	s_mov_b64 s[98:99], s[100:101]
	v_cvt_pk_bf16_f32 v244, v128, v129
	v_cvt_pk_bf16_f32 v245, v130, v131
	v_cvt_pk_bf16_f32 v246, v124, v125
	v_cvt_pk_bf16_f32 v247, v126, v127
	v_mov_b64_e32 v[128:129], 0
	v_mov_b64_e32 v[130:131], 0
	v_mov_b64_e32 v[124:125], 0
	v_mov_b64_e32 v[126:127], 0
	global_store_dwordx4 v216, v[244:247], s[98:99]
	s_mul_i32 s16, s17, 1
	s_add_u32 s98, s100, s16
	s_addc_u32 s99, s101, 0
	v_cvt_pk_bf16_f32 v248, v120, v121
	v_cvt_pk_bf16_f32 v249, v122, v123
	v_cvt_pk_bf16_f32 v250, v116, v117
	v_cvt_pk_bf16_f32 v251, v118, v119
	v_mov_b64_e32 v[120:121], 0
	v_mov_b64_e32 v[122:123], 0
	v_mov_b64_e32 v[116:117], 0
	v_mov_b64_e32 v[118:119], 0
	global_store_dwordx4 v216, v[248:251], s[98:99]
	s_mul_i32 s16, s17, 2
	s_add_u32 s98, s100, s16
	s_addc_u32 s99, s101, 0
	v_cvt_pk_bf16_f32 v204, v112, v113
	v_cvt_pk_bf16_f32 v205, v114, v115
	v_cvt_pk_bf16_f32 v206, v108, v109
	v_cvt_pk_bf16_f32 v207, v110, v111
	v_mov_b64_e32 v[112:113], 0
	v_mov_b64_e32 v[114:115], 0
	v_mov_b64_e32 v[108:109], 0
	v_mov_b64_e32 v[110:111], 0
	global_store_dwordx4 v216, v[204:207], s[98:99]
	s_mul_i32 s16, s17, 3
	s_add_u32 s98, s100, s16
	s_addc_u32 s99, s101, 0
	v_cvt_pk_bf16_f32 v132, v104, v105
	v_cvt_pk_bf16_f32 v133, v106, v107
	v_cvt_pk_bf16_f32 v134, v100, v101
	v_cvt_pk_bf16_f32 v135, v102, v103
	v_mov_b64_e32 v[104:105], 0
	v_mov_b64_e32 v[106:107], 0
	v_mov_b64_e32 v[100:101], 0
	v_mov_b64_e32 v[102:103], 0
	global_store_dwordx4 v216, v[132:135], s[98:99]
	s_mul_i32 s16, s17, 8
	s_add_u32 s98, s100, s16
	s_addc_u32 s99, s101, 0
	v_cvt_pk_bf16_f32 v136, v60, v61
	v_cvt_pk_bf16_f32 v137, v62, v63
	v_cvt_pk_bf16_f32 v138, v56, v57
	v_cvt_pk_bf16_f32 v139, v58, v59
	v_mov_b64_e32 v[60:61], 0
	v_mov_b64_e32 v[62:63], 0
	v_mov_b64_e32 v[56:57], 0
	v_mov_b64_e32 v[58:59], 0
	global_store_dwordx4 v216, v[136:139], s[98:99]
	s_mul_i32 s16, s17, 9
	s_add_u32 s98, s100, s16
	s_addc_u32 s99, s101, 0
	v_cvt_pk_bf16_f32 v160, v52, v53
	v_cvt_pk_bf16_f32 v161, v54, v55
	v_cvt_pk_bf16_f32 v162, v48, v49
	v_cvt_pk_bf16_f32 v163, v50, v51
	v_mov_b64_e32 v[52:53], 0
	v_mov_b64_e32 v[54:55], 0
	v_mov_b64_e32 v[48:49], 0
	v_mov_b64_e32 v[50:51], 0
	global_store_dwordx4 v216, v[160:163], s[98:99]
	s_mul_i32 s16, s17, 10
	s_add_u32 s98, s100, s16
	s_addc_u32 s99, s101, 0
	v_cvt_pk_bf16_f32 v164, v44, v45
	v_cvt_pk_bf16_f32 v165, v46, v47
	v_cvt_pk_bf16_f32 v166, v40, v41
	v_cvt_pk_bf16_f32 v167, v42, v43
	v_mov_b64_e32 v[44:45], 0
	v_mov_b64_e32 v[46:47], 0
	v_mov_b64_e32 v[40:41], 0
	v_mov_b64_e32 v[42:43], 0
	global_store_dwordx4 v216, v[164:167], s[98:99]
	s_mul_i32 s16, s17, 11
	s_add_u32 s98, s100, s16
	s_addc_u32 s99, s101, 0
	v_cvt_pk_bf16_f32 v168, v36, v37
	v_cvt_pk_bf16_f32 v169, v38, v39
	v_cvt_pk_bf16_f32 v170, v32, v33
	v_cvt_pk_bf16_f32 v171, v34, v35
	v_mov_b64_e32 v[36:37], 0
	v_mov_b64_e32 v[38:39], 0
	v_mov_b64_e32 v[32:33], 0
	v_mov_b64_e32 v[34:35], 0
	global_store_dwordx4 v216, v[168:171], s[98:99]
	s_mov_b64 s[98:99], s[100:101]
	v_cvt_pk_bf16_f32 v244, v92, v93
	v_cvt_pk_bf16_f32 v245, v94, v95
	v_cvt_pk_bf16_f32 v246, v88, v89
	v_cvt_pk_bf16_f32 v247, v90, v91
	v_mov_b64_e32 v[92:93], 0
	v_mov_b64_e32 v[94:95], 0
	v_mov_b64_e32 v[88:89], 0
	v_mov_b64_e32 v[90:91], 0
	global_store_dwordx4 v216, v[244:247], s[98:99] offset:256
	s_mul_i32 s16, s17, 1
	s_add_u32 s98, s100, s16
	s_addc_u32 s99, s101, 0
	v_cvt_pk_bf16_f32 v248, v84, v85
	v_cvt_pk_bf16_f32 v249, v86, v87
	v_cvt_pk_bf16_f32 v250, v80, v81
	v_cvt_pk_bf16_f32 v251, v82, v83
	v_mov_b64_e32 v[84:85], 0
	v_mov_b64_e32 v[86:87], 0
	v_mov_b64_e32 v[80:81], 0
	v_mov_b64_e32 v[82:83], 0
	global_store_dwordx4 v216, v[248:251], s[98:99] offset:256
	s_mul_i32 s16, s17, 2
	s_add_u32 s98, s100, s16
	s_addc_u32 s99, s101, 0
	v_cvt_pk_bf16_f32 v204, v76, v77
	v_cvt_pk_bf16_f32 v205, v78, v79
	v_cvt_pk_bf16_f32 v206, v72, v73
	v_cvt_pk_bf16_f32 v207, v74, v75
	v_mov_b64_e32 v[76:77], 0
	v_mov_b64_e32 v[78:79], 0
	v_mov_b64_e32 v[72:73], 0
	v_mov_b64_e32 v[74:75], 0
	global_store_dwordx4 v216, v[204:207], s[98:99] offset:256
	s_mul_i32 s16, s17, 3
	s_add_u32 s98, s100, s16
	s_addc_u32 s99, s101, 0
	v_cvt_pk_bf16_f32 v132, v68, v69
	v_cvt_pk_bf16_f32 v133, v70, v71
	v_cvt_pk_bf16_f32 v134, v64, v65
	v_cvt_pk_bf16_f32 v135, v66, v67
	v_mov_b64_e32 v[68:69], 0
	v_mov_b64_e32 v[70:71], 0
	v_mov_b64_e32 v[64:65], 0
	v_mov_b64_e32 v[66:67], 0
	global_store_dwordx4 v216, v[132:135], s[98:99] offset:256
	s_mul_i32 s16, s17, 8
	s_add_u32 s98, s100, s16
	s_addc_u32 s99, s101, 0
	v_cvt_pk_bf16_f32 v136, v28, v29
	v_cvt_pk_bf16_f32 v137, v30, v31
	v_cvt_pk_bf16_f32 v138, v24, v25
	v_cvt_pk_bf16_f32 v139, v26, v27
	v_mov_b64_e32 v[28:29], 0
	v_mov_b64_e32 v[30:31], 0
	v_mov_b64_e32 v[24:25], 0
	v_mov_b64_e32 v[26:27], 0
	global_store_dwordx4 v216, v[136:139], s[98:99] offset:256
	s_mul_i32 s16, s17, 9
	s_add_u32 s98, s100, s16
	s_addc_u32 s99, s101, 0
	v_cvt_pk_bf16_f32 v160, v20, v21
	v_cvt_pk_bf16_f32 v161, v22, v23
	v_cvt_pk_bf16_f32 v162, v16, v17
	v_cvt_pk_bf16_f32 v163, v18, v19
	v_mov_b64_e32 v[20:21], 0
	v_mov_b64_e32 v[22:23], 0
	v_mov_b64_e32 v[16:17], 0
	v_mov_b64_e32 v[18:19], 0
	global_store_dwordx4 v216, v[160:163], s[98:99] offset:256
	s_mul_i32 s16, s17, 10
	s_add_u32 s98, s100, s16
	s_addc_u32 s99, s101, 0
	v_cvt_pk_bf16_f32 v164, v12, v13
	v_cvt_pk_bf16_f32 v165, v14, v15
	v_cvt_pk_bf16_f32 v166, v8, v9
	v_cvt_pk_bf16_f32 v167, v10, v11
	v_mov_b64_e32 v[12:13], 0
	v_mov_b64_e32 v[14:15], 0
	v_mov_b64_e32 v[8:9], 0
	v_mov_b64_e32 v[10:11], 0
	global_store_dwordx4 v216, v[164:167], s[98:99] offset:256
	s_mul_i32 s16, s17, 11
	s_add_u32 s98, s100, s16
	s_addc_u32 s99, s101, 0
	v_cvt_pk_bf16_f32 v168, v4, v5
	v_cvt_pk_bf16_f32 v169, v6, v7
	v_cvt_pk_bf16_f32 v170, v0, v1
	v_cvt_pk_bf16_f32 v171, v2, v3
	v_mov_b64_e32 v[4:5], 0
	v_mov_b64_e32 v[6:7], 0
	v_mov_b64_e32 v[0:1], 0
	v_mov_b64_e32 v[2:3], 0
	global_store_dwordx4 v216, v[168:171], s[98:99] offset:256
	s_branch .Lep_done
; __device__ __forceinline__ unsigned cvt_pk_bf16(float lo, float hi) { unsigned r; asm volatile("v_cvt_pk_bf16_f32 %0, %1, %2" : "=v"(r) : "v"(lo), "v"(hi)); return r; }
; __device__ __forceinline__ void epi_store(const f32x4 (&acc)[2][2][4][2], const Unit& u, int wr, int wc, int fr, int fq, const EpiP& e) {
;     ...
;             const int c = col0 + bj * HALF;
;             f32x4 cs0 = {1.f, 1.f, 1.f, 1.f}, cs1 = {1.f, 1.f, 1.f, 1.f};
;             if (e.mode == 0 && e.colscale) { cs0 = *(const f32x4*)(e.colscale + c); cs1 = *(const f32x4*)(e.colscale + c + 4); }
; #pragma unroll
;             for (int ai = 0; ai < 2; ++ai)
; #pragma unroll
;                 for (int m = 0; m < 4; ++m) {
;                     const int row = row0 + ai * HALF + m * 16;
;                     f32x4 v0 = acc[ai][bj][m][0], v1 = acc[ai][bj][m][1];
;                     if (e.mode == 1) {
; #pragma unroll
;                         for (int j = 0; j < 4; ++j) { const float a = fmaxf(v0[j], 0.f), b = fmaxf(v1[j], 0.f); v0[j] = a * a; v1[j] = b * b; }
;                     } else { v0 *= cs0; v1 *= cs1; }
;                     bf16_t* rowp = (u.ks < 0 ? e.O + (size_t)row * e.ldo : e.Opart + ((size_t)u.ks * MCTX + (row - MLAT)) * 1024) + c;
;                     if (e.mode == 1)
;                         rowp = (bf16_t*)((char*)e.O + ((size_t)(u.pm * 64 + u.pn * 4 + bj * 2 + (wc >> 1))) * 32768 + ai * 16384 + (((wr * 4 + m) * 2 + (wc & 1)) * 1024) + (fr * 4 + fq) * 16);
;                     u32x4 w; w.x = cvt_pk_bf16(v0[0], v0[1]); w.y = cvt_pk_bf16(v0[2], v0[3]); w.z = cvt_pk_bf16(v1[0], v1[1]); w.w = cvt_pk_bf16(v1[2], v1[3]);
;                     *(u32x4*)rowp = w;
; __device__ __forceinline__ void gemm_phase(LAS unsigned char* lds, const GemmP g, const EpiP e) {
;     ...
; #pragma unroll
;         for (int a = 0; a < 2; ++a)
; #pragma unroll
;             for (int b = 0; b < 2; ++b)
; #pragma unroll
;                 for (int m = 0; m < 4; ++m)
; #pragma unroll
;                     for (int n = 0; n < 2; ++n) acc[a][b][m][n] = (f32x4){0.f, 0.f, 0.f, 0.f};
.Lep0_cs:
	v_readlane_b32 s20, v255, 5
	v_readlane_b32 s21, v255, 6
	s_lshl_b32 s19, s85, 10
	s_add_u32 s20, s20, s19
	s_addc_u32 s21, s21, 0
	v_lshlrev_b32_e32 v217, 2, v218
	s_nop 1
	global_load_dwordx4 v[220:223], v217, s[20:21]
	global_load_dwordx4 v[224:227], v217, s[20:21] offset:16
	global_load_dwordx4 v[228:231], v217, s[20:21] offset:512
	global_load_dwordx4 v[232:235], v217, s[20:21] offset:528
	s_waitcnt vmcnt(0)
	s_mov_b64 s[98:99], s[100:101]
	v_pk_mul_f32 v[236:237], v[128:129], v[220:221]
	v_pk_mul_f32 v[238:239], v[130:131], v[222:223]
	v_pk_mul_f32 v[240:241], v[124:125], v[224:225]
	v_pk_mul_f32 v[242:243], v[126:127], v[226:227]
	v_mov_b64_e32 v[128:129], 0
	v_mov_b64_e32 v[130:131], 0
	v_mov_b64_e32 v[124:125], 0
	v_mov_b64_e32 v[126:127], 0
	v_cvt_pk_bf16_f32 v244, v236, v237
	v_cvt_pk_bf16_f32 v245, v238, v239
	v_cvt_pk_bf16_f32 v246, v240, v241
	v_cvt_pk_bf16_f32 v247, v242, v243
	global_store_dwordx4 v216, v[244:247], s[98:99]
	s_mul_i32 s16, s17, 1
	s_add_u32 s98, s100, s16
	s_addc_u32 s99, s101, 0
	v_pk_mul_f32 v[236:237], v[120:121], v[220:221]
	v_pk_mul_f32 v[238:239], v[122:123], v[222:223]
	v_pk_mul_f32 v[240:241], v[116:117], v[224:225]
	v_pk_mul_f32 v[242:243], v[118:119], v[226:227]
	v_mov_b64_e32 v[120:121], 0
	v_mov_b64_e32 v[122:123], 0
	v_mov_b64_e32 v[116:117], 0
	v_mov_b64_e32 v[118:119], 0
	v_cvt_pk_bf16_f32 v248, v236, v237
	v_cvt_pk_bf16_f32 v249, v238, v239
	v_cvt_pk_bf16_f32 v250, v240, v241
	v_cvt_pk_bf16_f32 v251, v242, v243
	global_store_dwordx4 v216, v[248:251], s[98:99]
	s_mul_i32 s16, s17, 2
	s_add_u32 s98, s100, s16
	s_addc_u32 s99, s101, 0
	v_pk_mul_f32 v[236:237], v[112:113], v[220:221]
	v_pk_mul_f32 v[238:239], v[114:115], v[222:223]
	v_pk_mul_f32 v[240:241], v[108:109], v[224:225]
	v_pk_mul_f32 v[242:243], v[110:111], v[226:227]
	v_mov_b64_e32 v[112:113], 0
	v_mov_b64_e32 v[114:115], 0
	v_mov_b64_e32 v[108:109], 0
	v_mov_b64_e32 v[110:111], 0
	v_cvt_pk_bf16_f32 v204, v236, v237
	v_cvt_pk_bf16_f32 v205, v238, v239
	v_cvt_pk_bf16_f32 v206, v240, v241
	v_cvt_pk_bf16_f32 v207, v242, v243
	global_store_dwordx4 v216, v[204:207], s[98:99]
	s_mul_i32 s16, s17, 3
	s_add_u32 s98, s100, s16
	s_addc_u32 s99, s101, 0
	v_pk_mul_f32 v[236:237], v[104:105], v[220:221]
	v_pk_mul_f32 v[238:239], v[106:107], v[222:223]
	v_pk_mul_f32 v[240:241], v[100:101], v[224:225]
	v_pk_mul_f32 v[242:243], v[102:103], v[226:227]
	v_mov_b64_e32 v[104:105], 0
	v_mov_b64_e32 v[106:107], 0
	v_mov_b64_e32 v[100:101], 0
	v_mov_b64_e32 v[102:103], 0
	v_cvt_pk_bf16_f32 v132, v236, v237
	v_cvt_pk_bf16_f32 v133, v238, v239
	v_cvt_pk_bf16_f32 v134, v240, v241
	v_cvt_pk_bf16_f32 v135, v242, v243
	global_store_dwordx4 v216, v[132:135], s[98:99]
	s_mul_i32 s16, s17, 8
	s_add_u32 s98, s100, s16
	s_addc_u32 s99, s101, 0
	v_pk_mul_f32 v[236:237], v[60:61], v[220:221]
	v_pk_mul_f32 v[238:239], v[62:63], v[222:223]
	v_pk_mul_f32 v[240:241], v[56:57], v[224:225]
	v_pk_mul_f32 v[242:243], v[58:59], v[226:227]
	v_mov_b64_e32 v[60:61], 0
	v_mov_b64_e32 v[62:63], 0
	v_mov_b64_e32 v[56:57], 0
	v_mov_b64_e32 v[58:59], 0
	v_cvt_pk_bf16_f32 v244, v236, v237
	v_cvt_pk_bf16_f32 v245, v238, v239
	v_cvt_pk_bf16_f32 v246, v240, v241
	v_cvt_pk_bf16_f32 v247, v242, v243
	global_store_dwordx4 v216, v[244:247], s[98:99]
	s_mul_i32 s16, s17, 9
	s_add_u32 s98, s100, s16
	s_addc_u32 s99, s101, 0
	v_pk_mul_f32 v[236:237], v[52:53], v[220:221]
	v_pk_mul_f32 v[238:239], v[54:55], v[222:223]
	v_pk_mul_f32 v[240:241], v[48:49], v[224:225]
	v_pk_mul_f32 v[242:243], v[50:51], v[226:227]
	v_mov_b64_e32 v[52:53], 0
	v_mov_b64_e32 v[54:55], 0
	v_mov_b64_e32 v[48:49], 0
	v_mov_b64_e32 v[50:51], 0
	v_cvt_pk_bf16_f32 v248, v236, v237
	v_cvt_pk_bf16_f32 v249, v238, v239
	v_cvt_pk_bf16_f32 v250, v240, v241
	v_cvt_pk_bf16_f32 v251, v242, v243
	global_store_dwordx4 v216, v[248:251], s[98:99]
	s_mul_i32 s16, s17, 10
	s_add_u32 s98, s100, s16
	s_addc_u32 s99, s101, 0
	v_pk_mul_f32 v[236:237], v[44:45], v[220:221]
	v_pk_mul_f32 v[238:239], v[46:47], v[222:223]
	v_pk_mul_f32 v[240:241], v[40:41], v[224:225]
	v_pk_mul_f32 v[242:243], v[42:43], v[226:227]
	v_mov_b64_e32 v[44:45], 0
	v_mov_b64_e32 v[46:47], 0
	v_mov_b64_e32 v[40:41], 0
	v_mov_b64_e32 v[42:43], 0
	v_cvt_pk_bf16_f32 v204, v236, v237
	v_cvt_pk_bf16_f32 v205, v238, v239
	v_cvt_pk_bf16_f32 v206, v240, v241
	v_cvt_pk_bf16_f32 v207, v242, v243
	global_store_dwordx4 v216, v[204:207], s[98:99]
	s_mul_i32 s16, s17, 11
	s_add_u32 s98, s100, s16
	s_addc_u32 s99, s101, 0
	v_pk_mul_f32 v[236:237], v[36:37], v[220:221]
	v_pk_mul_f32 v[238:239], v[38:39], v[222:223]
	v_pk_mul_f32 v[240:241], v[32:33], v[224:225]
	v_pk_mul_f32 v[242:243], v[34:35], v[226:227]
	v_mov_b64_e32 v[36:37], 0
	v_mov_b64_e32 v[38:39], 0
	v_mov_b64_e32 v[32:33], 0
	v_mov_b64_e32 v[34:35], 0
	v_cvt_pk_bf16_f32 v132, v236, v237
	v_cvt_pk_bf16_f32 v133, v238, v239
	v_cvt_pk_bf16_f32 v134, v240, v241
	v_cvt_pk_bf16_f32 v135, v242, v243
	global_store_dwordx4 v216, v[132:135], s[98:99]
	s_mov_b64 s[98:99], s[100:101]
	v_pk_mul_f32 v[236:237], v[92:93], v[228:229]
	v_pk_mul_f32 v[238:239], v[94:95], v[230:231]
	v_pk_mul_f32 v[240:241], v[88:89], v[232:233]
	v_pk_mul_f32 v[242:243], v[90:91], v[234:235]
	v_mov_b64_e32 v[92:93], 0
	v_mov_b64_e32 v[94:95], 0
	v_mov_b64_e32 v[88:89], 0
	v_mov_b64_e32 v[90:91], 0
	v_cvt_pk_bf16_f32 v244, v236, v237
	v_cvt_pk_bf16_f32 v245, v238, v239
	v_cvt_pk_bf16_f32 v246, v240, v241
	v_cvt_pk_bf16_f32 v247, v242, v243
	global_store_dwordx4 v216, v[244:247], s[98:99] offset:256
	s_mul_i32 s16, s17, 1
	s_add_u32 s98, s100, s16
	s_addc_u32 s99, s101, 0
	v_pk_mul_f32 v[236:237], v[84:85], v[228:229]
	v_pk_mul_f32 v[238:239], v[86:87], v[230:231]
; __device__ __forceinline__ unsigned cvt_pk_bf16(float lo, float hi) { unsigned r; asm volatile("v_cvt_pk_bf16_f32 %0, %1, %2" : "=v"(r) : "v"(lo), "v"(hi)); return r; }
; __device__ __forceinline__ void epi_store(const f32x4 (&acc)[2][2][4][2], const Unit& u, int wr, int wc, int fr, int fq, const EpiP& e) {
;     ...
;                 for (int m = 0; m < 4; ++m) {
;                     const int row = row0 + ai * HALF + m * 16;
;                     f32x4 v0 = acc[ai][bj][m][0], v1 = acc[ai][bj][m][1];
;                     if (e.mode == 1) {
; #pragma unroll
;                         for (int j = 0; j < 4; ++j) { const float a = fmaxf(v0[j], 0.f), b = fmaxf(v1[j], 0.f); v0[j] = a * a; v1[j] = b * b; }
;                     } else { v0 *= cs0; v1 *= cs1; }
;                     bf16_t* rowp = (u.ks < 0 ? e.O + (size_t)row * e.ldo : e.Opart + ((size_t)u.ks * MCTX + (row - MLAT)) * 1024) + c;
;                     if (e.mode == 1)
;                         rowp = (bf16_t*)((char*)e.O + ((size_t)(u.pm * 64 + u.pn * 4 + bj * 2 + (wc >> 1))) * 32768 + ai * 16384 + (((wr * 4 + m) * 2 + (wc & 1)) * 1024) + (fr * 4 + fq) * 16);
;                     u32x4 w; w.x = cvt_pk_bf16(v0[0], v0[1]); w.y = cvt_pk_bf16(v0[2], v0[3]); w.z = cvt_pk_bf16(v1[0], v1[1]); w.w = cvt_pk_bf16(v1[2], v1[3]);
;                     *(u32x4*)rowp = w;
; __device__ __forceinline__ void gemm_phase(LAS unsigned char* lds, const GemmP g, const EpiP e) {
;     ...
; #pragma unroll
;         for (int a = 0; a < 2; ++a)
; #pragma unroll
;             for (int b = 0; b < 2; ++b)
; #pragma unroll
;                 for (int m = 0; m < 4; ++m)
; #pragma unroll
;                     for (int n = 0; n < 2; ++n) acc[a][b][m][n] = (f32x4){0.f, 0.f, 0.f, 0.f};
	v_pk_mul_f32 v[240:241], v[80:81], v[232:233]
	v_pk_mul_f32 v[242:243], v[82:83], v[234:235]
	v_mov_b64_e32 v[84:85], 0
	v_mov_b64_e32 v[86:87], 0
	v_mov_b64_e32 v[80:81], 0
	v_mov_b64_e32 v[82:83], 0
	v_cvt_pk_bf16_f32 v248, v236, v237
	v_cvt_pk_bf16_f32 v249, v238, v239
	v_cvt_pk_bf16_f32 v250, v240, v241
	v_cvt_pk_bf16_f32 v251, v242, v243
	global_store_dwordx4 v216, v[248:251], s[98:99] offset:256
	s_mul_i32 s16, s17, 2
	s_add_u32 s98, s100, s16
	s_addc_u32 s99, s101, 0
	v_pk_mul_f32 v[236:237], v[76:77], v[228:229]
	v_pk_mul_f32 v[238:239], v[78:79], v[230:231]
	v_pk_mul_f32 v[240:241], v[72:73], v[232:233]
	v_pk_mul_f32 v[242:243], v[74:75], v[234:235]
	v_mov_b64_e32 v[76:77], 0
	v_mov_b64_e32 v[78:79], 0
	v_mov_b64_e32 v[72:73], 0
	v_mov_b64_e32 v[74:75], 0
	v_cvt_pk_bf16_f32 v204, v236, v237
	v_cvt_pk_bf16_f32 v205, v238, v239
	v_cvt_pk_bf16_f32 v206, v240, v241
	v_cvt_pk_bf16_f32 v207, v242, v243
	global_store_dwordx4 v216, v[204:207], s[98:99] offset:256
	s_mul_i32 s16, s17, 3
	s_add_u32 s98, s100, s16
	s_addc_u32 s99, s101, 0
	v_pk_mul_f32 v[236:237], v[68:69], v[228:229]
	v_pk_mul_f32 v[238:239], v[70:71], v[230:231]
	v_pk_mul_f32 v[240:241], v[64:65], v[232:233]
	v_pk_mul_f32 v[242:243], v[66:67], v[234:235]
	v_mov_b64_e32 v[68:69], 0
	v_mov_b64_e32 v[70:71], 0
	v_mov_b64_e32 v[64:65], 0
	v_mov_b64_e32 v[66:67], 0
	v_cvt_pk_bf16_f32 v132, v236, v237
	v_cvt_pk_bf16_f32 v133, v238, v239
	v_cvt_pk_bf16_f32 v134, v240, v241
	v_cvt_pk_bf16_f32 v135, v242, v243
	global_store_dwordx4 v216, v[132:135], s[98:99] offset:256
	s_mul_i32 s16, s17, 8
	s_add_u32 s98, s100, s16
	s_addc_u32 s99, s101, 0
	v_pk_mul_f32 v[236:237], v[28:29], v[228:229]
	v_pk_mul_f32 v[238:239], v[30:31], v[230:231]
	v_pk_mul_f32 v[240:241], v[24:25], v[232:233]
	v_pk_mul_f32 v[242:243], v[26:27], v[234:235]
	v_mov_b64_e32 v[28:29], 0
	v_mov_b64_e32 v[30:31], 0
	v_mov_b64_e32 v[24:25], 0
	v_mov_b64_e32 v[26:27], 0
	v_cvt_pk_bf16_f32 v244, v236, v237
	v_cvt_pk_bf16_f32 v245, v238, v239
	v_cvt_pk_bf16_f32 v246, v240, v241
	v_cvt_pk_bf16_f32 v247, v242, v243
	global_store_dwordx4 v216, v[244:247], s[98:99] offset:256
	s_mul_i32 s16, s17, 9
	s_add_u32 s98, s100, s16
	s_addc_u32 s99, s101, 0
	v_pk_mul_f32 v[236:237], v[20:21], v[228:229]
	v_pk_mul_f32 v[238:239], v[22:23], v[230:231]
	v_pk_mul_f32 v[240:241], v[16:17], v[232:233]
	v_pk_mul_f32 v[242:243], v[18:19], v[234:235]
	v_mov_b64_e32 v[20:21], 0
	v_mov_b64_e32 v[22:23], 0
	v_mov_b64_e32 v[16:17], 0
	v_mov_b64_e32 v[18:19], 0
	v_cvt_pk_bf16_f32 v248, v236, v237
	v_cvt_pk_bf16_f32 v249, v238, v239
	v_cvt_pk_bf16_f32 v250, v240, v241
	v_cvt_pk_bf16_f32 v251, v242, v243
	global_store_dwordx4 v216, v[248:251], s[98:99] offset:256
	s_mul_i32 s16, s17, 10
	s_add_u32 s98, s100, s16
	s_addc_u32 s99, s101, 0
	v_pk_mul_f32 v[236:237], v[12:13], v[228:229]
	v_pk_mul_f32 v[238:239], v[14:15], v[230:231]
	v_pk_mul_f32 v[240:241], v[8:9], v[232:233]
	v_pk_mul_f32 v[242:243], v[10:11], v[234:235]
	v_mov_b64_e32 v[12:13], 0
	v_mov_b64_e32 v[14:15], 0
	v_mov_b64_e32 v[8:9], 0
	v_mov_b64_e32 v[10:11], 0
	v_cvt_pk_bf16_f32 v204, v236, v237
	v_cvt_pk_bf16_f32 v205, v238, v239
	v_cvt_pk_bf16_f32 v206, v240, v241
	v_cvt_pk_bf16_f32 v207, v242, v243
	global_store_dwordx4 v216, v[204:207], s[98:99] offset:256
	s_mul_i32 s16, s17, 11
	s_add_u32 s98, s100, s16
	s_addc_u32 s99, s101, 0
	v_pk_mul_f32 v[236:237], v[4:5], v[228:229]
	v_pk_mul_f32 v[238:239], v[6:7], v[230:231]
	v_pk_mul_f32 v[240:241], v[0:1], v[232:233]
	v_pk_mul_f32 v[242:243], v[2:3], v[234:235]
	v_mov_b64_e32 v[4:5], 0
	v_mov_b64_e32 v[6:7], 0
	v_mov_b64_e32 v[0:1], 0
	v_mov_b64_e32 v[2:3], 0
	v_cvt_pk_bf16_f32 v132, v236, v237
	v_cvt_pk_bf16_f32 v133, v238, v239
	v_cvt_pk_bf16_f32 v134, v240, v241
	v_cvt_pk_bf16_f32 v135, v242, v243
	global_store_dwordx4 v216, v[132:135], s[98:99] offset:256
	s_branch .Lep_done
.Lep1_setup:
	s_lshl_b32 s16, s87, 6
	s_lshl_b32 s17, s85, 2
	s_add_i32 s16, s16, s17
	s_lshl_b32 s16, s16, 15
	s_add_u32 s100, s74, s16
	s_addc_u32 s101, s75, 0
	v_lshl_or_b32 v217, v217, 2, v219
	v_lshlrev_b32_e32 v217, 4, v217
	v_lshl_or_b32 v217, v218, 13, v217
	v_bfe_u32 v218, v159, 6, 1
	v_lshl_or_b32 v217, v218, 10, v217
	v_bfe_u32 v218, v159, 7, 1
	v_lshl_or_b32 v216, v218, 15, v217
	s_mov_b64 s[98:99], s[100:101]
	v_max_f32_e32 v220, 0, v128
	v_max_f32_e32 v221, 0, v129
	v_max_f32_e32 v222, 0, v130
	v_max_f32_e32 v223, 0, v131
	v_max_f32_e32 v224, 0, v124
	v_max_f32_e32 v225, 0, v125
	v_max_f32_e32 v226, 0, v126
	v_max_f32_e32 v227, 0, v127
	v_mov_b64_e32 v[128:129], 0
	v_mov_b64_e32 v[130:131], 0
	v_mov_b64_e32 v[124:125], 0
	v_mov_b64_e32 v[126:127], 0
	v_pk_mul_f32 v[220:221], v[220:221], v[220:221]
	v_pk_mul_f32 v[222:223], v[222:223], v[222:223]
	v_pk_mul_f32 v[224:225], v[224:225], v[224:225]
	v_pk_mul_f32 v[226:227], v[226:227], v[226:227]
	v_cvt_pk_bf16_f32 v204, v220, v221
	v_cvt_pk_bf16_f32 v205, v222, v223
	v_cvt_pk_bf16_f32 v206, v224, v225
	v_cvt_pk_bf16_f32 v207, v226, v227
	global_store_dwordx4 v216, v[204:207], s[98:99]
	s_add_u32 s98, s100, 0x800
	s_addc_u32 s99, s101, 0
	v_max_f32_e32 v228, 0, v120
	v_max_f32_e32 v229, 0, v121
	v_max_f32_e32 v230, 0, v122
	v_max_f32_e32 v231, 0, v123
	v_max_f32_e32 v232, 0, v116
	v_max_f32_e32 v233, 0, v117
	v_max_f32_e32 v234, 0, v118
	v_max_f32_e32 v235, 0, v119
	v_mov_b64_e32 v[120:121], 0
	v_mov_b64_e32 v[122:123], 0
	v_mov_b64_e32 v[116:117], 0
	v_mov_b64_e32 v[118:119], 0
	v_pk_mul_f32 v[228:229], v[228:229], v[228:229]
	v_pk_mul_f32 v[230:231], v[230:231], v[230:231]
	v_pk_mul_f32 v[232:233], v[232:233], v[232:233]
	v_pk_mul_f32 v[234:235], v[234:235], v[234:235]
	v_cvt_pk_bf16_f32 v132, v228, v229
; __device__ __forceinline__ unsigned cvt_pk_bf16(float lo, float hi) { unsigned r; asm volatile("v_cvt_pk_bf16_f32 %0, %1, %2" : "=v"(r) : "v"(lo), "v"(hi)); return r; }
; __device__ __forceinline__ void epi_store(const f32x4 (&acc)[2][2][4][2], const Unit& u, int wr, int wc, int fr, int fq, const EpiP& e) {
;     ...
;                     if (e.mode == 1) {
; #pragma unroll
;                         for (int j = 0; j < 4; ++j) { const float a = fmaxf(v0[j], 0.f), b = fmaxf(v1[j], 0.f); v0[j] = a * a; v1[j] = b * b; }
;                     } else { v0 *= cs0; v1 *= cs1; }
;                     bf16_t* rowp = (u.ks < 0 ? e.O + (size_t)row * e.ldo : e.Opart + ((size_t)u.ks * MCTX + (row - MLAT)) * 1024) + c;
;                     if (e.mode == 1)
;                         rowp = (bf16_t*)((char*)e.O + ((size_t)(u.pm * 64 + u.pn * 4 + bj * 2 + (wc >> 1))) * 32768 + ai * 16384 + (((wr * 4 + m) * 2 + (wc & 1)) * 1024) + (fr * 4 + fq) * 16);
;                     u32x4 w; w.x = cvt_pk_bf16(v0[0], v0[1]); w.y = cvt_pk_bf16(v0[2], v0[3]); w.z = cvt_pk_bf16(v1[0], v1[1]); w.w = cvt_pk_bf16(v1[2], v1[3]);
;                     *(u32x4*)rowp = w;
; __device__ __forceinline__ void gemm_phase(LAS unsigned char* lds, const GemmP g, const EpiP e) {
;     ...
; #pragma unroll
;         for (int a = 0; a < 2; ++a)
; #pragma unroll
;             for (int b = 0; b < 2; ++b)
; #pragma unroll
;                 for (int m = 0; m < 4; ++m)
; #pragma unroll
;                     for (int n = 0; n < 2; ++n) acc[a][b][m][n] = (f32x4){0.f, 0.f, 0.f, 0.f};
	v_cvt_pk_bf16_f32 v133, v230, v231
	v_cvt_pk_bf16_f32 v134, v232, v233
	v_cvt_pk_bf16_f32 v135, v234, v235
	global_store_dwordx4 v216, v[132:135], s[98:99]
	s_add_u32 s98, s100, 0x1000
	s_addc_u32 s99, s101, 0
	v_max_f32_e32 v220, 0, v112
	v_max_f32_e32 v221, 0, v113
	v_max_f32_e32 v222, 0, v114
	v_max_f32_e32 v223, 0, v115
	v_max_f32_e32 v224, 0, v108
	v_max_f32_e32 v225, 0, v109
	v_max_f32_e32 v226, 0, v110
	v_max_f32_e32 v227, 0, v111
	v_mov_b64_e32 v[112:113], 0
	v_mov_b64_e32 v[114:115], 0
	v_mov_b64_e32 v[108:109], 0
	v_mov_b64_e32 v[110:111], 0
	v_pk_mul_f32 v[220:221], v[220:221], v[220:221]
	v_pk_mul_f32 v[222:223], v[222:223], v[222:223]
	v_pk_mul_f32 v[224:225], v[224:225], v[224:225]
	v_pk_mul_f32 v[226:227], v[226:227], v[226:227]
	v_cvt_pk_bf16_f32 v136, v220, v221
	v_cvt_pk_bf16_f32 v137, v222, v223
	v_cvt_pk_bf16_f32 v138, v224, v225
	v_cvt_pk_bf16_f32 v139, v226, v227
	global_store_dwordx4 v216, v[136:139], s[98:99]
	s_add_u32 s98, s100, 0x1800
	s_addc_u32 s99, s101, 0
	v_max_f32_e32 v228, 0, v104
	v_max_f32_e32 v229, 0, v105
	v_max_f32_e32 v230, 0, v106
	v_max_f32_e32 v231, 0, v107
	v_max_f32_e32 v232, 0, v100
	v_max_f32_e32 v233, 0, v101
	v_max_f32_e32 v234, 0, v102
	v_max_f32_e32 v235, 0, v103
	v_mov_b64_e32 v[104:105], 0
	v_mov_b64_e32 v[106:107], 0
	v_mov_b64_e32 v[100:101], 0
	v_mov_b64_e32 v[102:103], 0
	v_pk_mul_f32 v[228:229], v[228:229], v[228:229]
	v_pk_mul_f32 v[230:231], v[230:231], v[230:231]
	v_pk_mul_f32 v[232:233], v[232:233], v[232:233]
	v_pk_mul_f32 v[234:235], v[234:235], v[234:235]
	v_cvt_pk_bf16_f32 v160, v228, v229
	v_cvt_pk_bf16_f32 v161, v230, v231
	v_cvt_pk_bf16_f32 v162, v232, v233
	v_cvt_pk_bf16_f32 v163, v234, v235
	global_store_dwordx4 v216, v[160:163], s[98:99]
	s_add_u32 s98, s100, 0x4000
	s_addc_u32 s99, s101, 0
	v_max_f32_e32 v220, 0, v60
	v_max_f32_e32 v221, 0, v61
	v_max_f32_e32 v222, 0, v62
	v_max_f32_e32 v223, 0, v63
	v_max_f32_e32 v224, 0, v56
	v_max_f32_e32 v225, 0, v57
	v_max_f32_e32 v226, 0, v58
	v_max_f32_e32 v227, 0, v59
	v_mov_b64_e32 v[60:61], 0
	v_mov_b64_e32 v[62:63], 0
	v_mov_b64_e32 v[56:57], 0
	v_mov_b64_e32 v[58:59], 0
	v_pk_mul_f32 v[220:221], v[220:221], v[220:221]
	v_pk_mul_f32 v[222:223], v[222:223], v[222:223]
	v_pk_mul_f32 v[224:225], v[224:225], v[224:225]
	v_pk_mul_f32 v[226:227], v[226:227], v[226:227]
	v_cvt_pk_bf16_f32 v164, v220, v221
	v_cvt_pk_bf16_f32 v165, v222, v223
	v_cvt_pk_bf16_f32 v166, v224, v225
	v_cvt_pk_bf16_f32 v167, v226, v227
	global_store_dwordx4 v216, v[164:167], s[98:99]
	s_add_u32 s98, s100, 0x4800
	s_addc_u32 s99, s101, 0
	v_max_f32_e32 v228, 0, v52
	v_max_f32_e32 v229, 0, v53
	v_max_f32_e32 v230, 0, v54
	v_max_f32_e32 v231, 0, v55
	v_max_f32_e32 v232, 0, v48
	v_max_f32_e32 v233, 0, v49
	v_max_f32_e32 v234, 0, v50
	v_max_f32_e32 v235, 0, v51
	v_mov_b64_e32 v[52:53], 0
	v_mov_b64_e32 v[54:55], 0
	v_mov_b64_e32 v[48:49], 0
	v_mov_b64_e32 v[50:51], 0
	v_pk_mul_f32 v[228:229], v[228:229], v[228:229]
	v_pk_mul_f32 v[230:231], v[230:231], v[230:231]
	v_pk_mul_f32 v[232:233], v[232:233], v[232:233]
	v_pk_mul_f32 v[234:235], v[234:235], v[234:235]
	v_cvt_pk_bf16_f32 v168, v228, v229
	v_cvt_pk_bf16_f32 v169, v230, v231
	v_cvt_pk_bf16_f32 v170, v232, v233
	v_cvt_pk_bf16_f32 v171, v234, v235
	global_store_dwordx4 v216, v[168:171], s[98:99]
	s_add_u32 s98, s100, 0x5000
	s_addc_u32 s99, s101, 0
	v_max_f32_e32 v220, 0, v44
	v_max_f32_e32 v221, 0, v45
	v_max_f32_e32 v222, 0, v46
	v_max_f32_e32 v223, 0, v47
	v_max_f32_e32 v224, 0, v40
	v_max_f32_e32 v225, 0, v41
	v_max_f32_e32 v226, 0, v42
	v_max_f32_e32 v227, 0, v43
	v_mov_b64_e32 v[44:45], 0
	v_mov_b64_e32 v[46:47], 0
	v_mov_b64_e32 v[40:41], 0
	v_mov_b64_e32 v[42:43], 0
	v_pk_mul_f32 v[220:221], v[220:221], v[220:221]
	v_pk_mul_f32 v[222:223], v[222:223], v[222:223]
	v_pk_mul_f32 v[224:225], v[224:225], v[224:225]
	v_pk_mul_f32 v[226:227], v[226:227], v[226:227]
	v_cvt_pk_bf16_f32 v172, v220, v221
	v_cvt_pk_bf16_f32 v173, v222, v223
	v_cvt_pk_bf16_f32 v174, v224, v225
	v_cvt_pk_bf16_f32 v175, v226, v227
	global_store_dwordx4 v216, v[172:175], s[98:99]
	s_add_u32 s98, s100, 0x5800
	s_addc_u32 s99, s101, 0
	v_max_f32_e32 v228, 0, v36
	v_max_f32_e32 v229, 0, v37
	v_max_f32_e32 v230, 0, v38
	v_max_f32_e32 v231, 0, v39
	v_max_f32_e32 v232, 0, v32
	v_max_f32_e32 v233, 0, v33
	v_max_f32_e32 v234, 0, v34
	v_max_f32_e32 v235, 0, v35
	v_mov_b64_e32 v[36:37], 0
	v_mov_b64_e32 v[38:39], 0
	v_mov_b64_e32 v[32:33], 0
	v_mov_b64_e32 v[34:35], 0
	v_pk_mul_f32 v[228:229], v[228:229], v[228:229]
	v_pk_mul_f32 v[230:231], v[230:231], v[230:231]
	v_pk_mul_f32 v[232:233], v[232:233], v[232:233]
	v_pk_mul_f32 v[234:235], v[234:235], v[234:235]
	v_cvt_pk_bf16_f32 v248, v228, v229
	v_cvt_pk_bf16_f32 v249, v230, v231
	v_cvt_pk_bf16_f32 v250, v232, v233
	v_cvt_pk_bf16_f32 v251, v234, v235
	global_store_dwordx4 v216, v[248:251], s[98:99]
	s_add_u32 s98, s100, 0x10000
	s_addc_u32 s99, s101, 0
	v_max_f32_e32 v220, 0, v92
	v_max_f32_e32 v221, 0, v93
	v_max_f32_e32 v222, 0, v94
	v_max_f32_e32 v223, 0, v95
	v_max_f32_e32 v224, 0, v88
	v_max_f32_e32 v225, 0, v89
	v_max_f32_e32 v226, 0, v90
	v_max_f32_e32 v227, 0, v91
	v_mov_b64_e32 v[92:93], 0
	v_mov_b64_e32 v[94:95], 0
	v_mov_b64_e32 v[88:89], 0
	v_mov_b64_e32 v[90:91], 0
	v_pk_mul_f32 v[220:221], v[220:221], v[220:221]
	v_pk_mul_f32 v[222:223], v[222:223], v[222:223]
	v_pk_mul_f32 v[224:225], v[224:225], v[224:225]
	v_pk_mul_f32 v[226:227], v[226:227], v[226:227]
	v_cvt_pk_bf16_f32 v204, v220, v221
	v_cvt_pk_bf16_f32 v205, v222, v223
	v_cvt_pk_bf16_f32 v206, v224, v225
; __device__ __forceinline__ unsigned cvt_pk_bf16(float lo, float hi) { unsigned r; asm volatile("v_cvt_pk_bf16_f32 %0, %1, %2" : "=v"(r) : "v"(lo), "v"(hi)); return r; }
; __device__ __forceinline__ void epi_store(const f32x4 (&acc)[2][2][4][2], const Unit& u, int wr, int wc, int fr, int fq, const EpiP& e) {
;     ...
;                     if (e.mode == 1) {
; #pragma unroll
;                         for (int j = 0; j < 4; ++j) { const float a = fmaxf(v0[j], 0.f), b = fmaxf(v1[j], 0.f); v0[j] = a * a; v1[j] = b * b; }
;                     } else { v0 *= cs0; v1 *= cs1; }
;                     bf16_t* rowp = (u.ks < 0 ? e.O + (size_t)row * e.ldo : e.Opart + ((size_t)u.ks * MCTX + (row - MLAT)) * 1024) + c;
;                     if (e.mode == 1)
;                         rowp = (bf16_t*)((char*)e.O + ((size_t)(u.pm * 64 + u.pn * 4 + bj * 2 + (wc >> 1))) * 32768 + ai * 16384 + (((wr * 4 + m) * 2 + (wc & 1)) * 1024) + (fr * 4 + fq) * 16);
;                     u32x4 w; w.x = cvt_pk_bf16(v0[0], v0[1]); w.y = cvt_pk_bf16(v0[2], v0[3]); w.z = cvt_pk_bf16(v1[0], v1[1]); w.w = cvt_pk_bf16(v1[2], v1[3]);
;                     *(u32x4*)rowp = w;
; __device__ __forceinline__ void gemm_phase(LAS unsigned char* lds, const GemmP g, const EpiP e) {
;     ...
; #pragma unroll
;         for (int a = 0; a < 2; ++a)
; #pragma unroll
;             for (int b = 0; b < 2; ++b)
; #pragma unroll
;                 for (int m = 0; m < 4; ++m)
; #pragma unroll
;                     for (int n = 0; n < 2; ++n) acc[a][b][m][n] = (f32x4){0.f, 0.f, 0.f, 0.f};
	v_cvt_pk_bf16_f32 v207, v226, v227
	global_store_dwordx4 v216, v[204:207], s[98:99]
	s_add_u32 s98, s100, 0x10800
	s_addc_u32 s99, s101, 0
	v_max_f32_e32 v228, 0, v84
	v_max_f32_e32 v229, 0, v85
	v_max_f32_e32 v230, 0, v86
	v_max_f32_e32 v231, 0, v87
	v_max_f32_e32 v232, 0, v80
	v_max_f32_e32 v233, 0, v81
	v_max_f32_e32 v234, 0, v82
	v_max_f32_e32 v235, 0, v83
	v_mov_b64_e32 v[84:85], 0
	v_mov_b64_e32 v[86:87], 0
	v_mov_b64_e32 v[80:81], 0
	v_mov_b64_e32 v[82:83], 0
	v_pk_mul_f32 v[228:229], v[228:229], v[228:229]
	v_pk_mul_f32 v[230:231], v[230:231], v[230:231]
	v_pk_mul_f32 v[232:233], v[232:233], v[232:233]
	v_pk_mul_f32 v[234:235], v[234:235], v[234:235]
	v_cvt_pk_bf16_f32 v132, v228, v229
	v_cvt_pk_bf16_f32 v133, v230, v231
	v_cvt_pk_bf16_f32 v134, v232, v233
	v_cvt_pk_bf16_f32 v135, v234, v235
	global_store_dwordx4 v216, v[132:135], s[98:99]
	s_add_u32 s98, s100, 0x11000
	s_addc_u32 s99, s101, 0
	v_max_f32_e32 v220, 0, v76
	v_max_f32_e32 v221, 0, v77
	v_max_f32_e32 v222, 0, v78
	v_max_f32_e32 v223, 0, v79
	v_max_f32_e32 v224, 0, v72
	v_max_f32_e32 v225, 0, v73
	v_max_f32_e32 v226, 0, v74
	v_max_f32_e32 v227, 0, v75
	v_mov_b64_e32 v[76:77], 0
	v_mov_b64_e32 v[78:79], 0
	v_mov_b64_e32 v[72:73], 0
	v_mov_b64_e32 v[74:75], 0
	v_pk_mul_f32 v[220:221], v[220:221], v[220:221]
	v_pk_mul_f32 v[222:223], v[222:223], v[222:223]
	v_pk_mul_f32 v[224:225], v[224:225], v[224:225]
	v_pk_mul_f32 v[226:227], v[226:227], v[226:227]
	v_cvt_pk_bf16_f32 v136, v220, v221
	v_cvt_pk_bf16_f32 v137, v222, v223
	v_cvt_pk_bf16_f32 v138, v224, v225
	v_cvt_pk_bf16_f32 v139, v226, v227
	global_store_dwordx4 v216, v[136:139], s[98:99]
	s_add_u32 s98, s100, 0x11800
	s_addc_u32 s99, s101, 0
	v_max_f32_e32 v228, 0, v68
	v_max_f32_e32 v229, 0, v69
	v_max_f32_e32 v230, 0, v70
	v_max_f32_e32 v231, 0, v71
	v_max_f32_e32 v232, 0, v64
	v_max_f32_e32 v233, 0, v65
	v_max_f32_e32 v234, 0, v66
	v_max_f32_e32 v235, 0, v67
	v_mov_b64_e32 v[68:69], 0
	v_mov_b64_e32 v[70:71], 0
	v_mov_b64_e32 v[64:65], 0
	v_mov_b64_e32 v[66:67], 0
	v_pk_mul_f32 v[228:229], v[228:229], v[228:229]
	v_pk_mul_f32 v[230:231], v[230:231], v[230:231]
	v_pk_mul_f32 v[232:233], v[232:233], v[232:233]
	v_pk_mul_f32 v[234:235], v[234:235], v[234:235]
	v_cvt_pk_bf16_f32 v160, v228, v229
	v_cvt_pk_bf16_f32 v161, v230, v231
	v_cvt_pk_bf16_f32 v162, v232, v233
	v_cvt_pk_bf16_f32 v163, v234, v235
	global_store_dwordx4 v216, v[160:163], s[98:99]
	s_add_u32 s98, s100, 0x14000
	s_addc_u32 s99, s101, 0
	v_max_f32_e32 v220, 0, v28
	v_max_f32_e32 v221, 0, v29
	v_max_f32_e32 v222, 0, v30
	v_max_f32_e32 v223, 0, v31
	v_max_f32_e32 v224, 0, v24
	v_max_f32_e32 v225, 0, v25
	v_max_f32_e32 v226, 0, v26
	v_max_f32_e32 v227, 0, v27
	v_mov_b64_e32 v[28:29], 0
	v_mov_b64_e32 v[30:31], 0
	v_mov_b64_e32 v[24:25], 0
	v_mov_b64_e32 v[26:27], 0
	v_pk_mul_f32 v[220:221], v[220:221], v[220:221]
	v_pk_mul_f32 v[222:223], v[222:223], v[222:223]
	v_pk_mul_f32 v[224:225], v[224:225], v[224:225]
	v_pk_mul_f32 v[226:227], v[226:227], v[226:227]
	v_cvt_pk_bf16_f32 v164, v220, v221
	v_cvt_pk_bf16_f32 v165, v222, v223
	v_cvt_pk_bf16_f32 v166, v224, v225
	v_cvt_pk_bf16_f32 v167, v226, v227
	global_store_dwordx4 v216, v[164:167], s[98:99]
	s_add_u32 s98, s100, 0x14800
	s_addc_u32 s99, s101, 0
	v_max_f32_e32 v228, 0, v20
	v_max_f32_e32 v229, 0, v21
	v_max_f32_e32 v230, 0, v22
	v_max_f32_e32 v231, 0, v23
	v_max_f32_e32 v232, 0, v16
	v_max_f32_e32 v233, 0, v17
	v_max_f32_e32 v234, 0, v18
	v_max_f32_e32 v235, 0, v19
	v_mov_b64_e32 v[20:21], 0
	v_mov_b64_e32 v[22:23], 0
	v_mov_b64_e32 v[16:17], 0
	v_mov_b64_e32 v[18:19], 0
	v_pk_mul_f32 v[228:229], v[228:229], v[228:229]
	v_pk_mul_f32 v[230:231], v[230:231], v[230:231]
	v_pk_mul_f32 v[232:233], v[232:233], v[232:233]
	v_pk_mul_f32 v[234:235], v[234:235], v[234:235]
	v_cvt_pk_bf16_f32 v168, v228, v229
	v_cvt_pk_bf16_f32 v169, v230, v231
	v_cvt_pk_bf16_f32 v170, v232, v233
	v_cvt_pk_bf16_f32 v171, v234, v235
	global_store_dwordx4 v216, v[168:171], s[98:99]
	s_add_u32 s98, s100, 0x15000
	s_addc_u32 s99, s101, 0
	v_max_f32_e32 v220, 0, v12
	v_max_f32_e32 v221, 0, v13
	v_max_f32_e32 v222, 0, v14
	v_max_f32_e32 v223, 0, v15
	v_max_f32_e32 v224, 0, v8
	v_max_f32_e32 v225, 0, v9
	v_max_f32_e32 v226, 0, v10
	v_max_f32_e32 v227, 0, v11
	v_mov_b64_e32 v[12:13], 0
	v_mov_b64_e32 v[14:15], 0
	v_mov_b64_e32 v[8:9], 0
	v_mov_b64_e32 v[10:11], 0
	v_pk_mul_f32 v[220:221], v[220:221], v[220:221]
	v_pk_mul_f32 v[222:223], v[222:223], v[222:223]
	v_pk_mul_f32 v[224:225], v[224:225], v[224:225]
	v_pk_mul_f32 v[226:227], v[226:227], v[226:227]
	v_cvt_pk_bf16_f32 v172, v220, v221
	v_cvt_pk_bf16_f32 v173, v222, v223
	v_cvt_pk_bf16_f32 v174, v224, v225
	v_cvt_pk_bf16_f32 v175, v226, v227
	global_store_dwordx4 v216, v[172:175], s[98:99]
	s_add_u32 s98, s100, 0x15800
	s_addc_u32 s99, s101, 0
	v_max_f32_e32 v228, 0, v4
	v_max_f32_e32 v229, 0, v5
	v_max_f32_e32 v230, 0, v6
	v_max_f32_e32 v231, 0, v7
	v_max_f32_e32 v232, 0, v0
	v_max_f32_e32 v233, 0, v1
	v_max_f32_e32 v234, 0, v2
	v_max_f32_e32 v235, 0, v3
	v_mov_b64_e32 v[4:5], 0
	v_mov_b64_e32 v[6:7], 0
	v_mov_b64_e32 v[0:1], 0
	v_mov_b64_e32 v[2:3], 0
	v_pk_mul_f32 v[228:229], v[228:229], v[228:229]
	v_pk_mul_f32 v[230:231], v[230:231], v[230:231]
	v_pk_mul_f32 v[232:233], v[232:233], v[232:233]
	v_pk_mul_f32 v[234:235], v[234:235], v[234:235]
	v_cvt_pk_bf16_f32 v248, v228, v229
	v_cvt_pk_bf16_f32 v249, v230, v231
	v_cvt_pk_bf16_f32 v250, v232, v233
	v_cvt_pk_bf16_f32 v251, v234, v235
	global_store_dwordx4 v216, v[248:251], s[98:99]
